# adaLN GEMV loop rewritten (48 row-loads in flight, fused fma in k order, bit-identical) and moved onto the workgroups with fewer weight-transposes
# speedup vs baseline: 1.0326x; 1.0151x over previous
.LBB0_18:
	v_readlane_b32 s34, v250, 2
	v_readlane_b32 s35, v250, 3
	s_load_dwordx2 s[46:47], s[34:35], 0x0
	s_load_dwordx2 s[12:13], s[34:35], 0x48
	s_and_b32 s77, s75, 0xffff
	s_and_b32 s81, s73, 0xffff
	s_mov_b32 s37, 0
	s_waitcnt lgkmcnt(0)
	s_and_b32 s57, s47, 0xffff
	s_add_u32 s2, s74, 0x100000
	v_writelane_b32 v250, s2, 7
	s_addc_u32 s2, s75, 0
	v_writelane_b32 v250, s2, 8
	s_load_dwordx4 s[40:43], s[34:35], 0x38
	v_readlane_b32 s22, v250, 0
	s_lshl_b32 s54, s22, 3
	s_add_u32 s6, s74, 0x3000000
	s_addc_u32 s7, s75, 0
	s_add_u32 s8, s74, 0x7000000
	s_addc_u32 s9, s75, 0
	s_lshl_b32 s24, s97, 3
	s_cmpk_eq_u32 s22, 0x100
	s_cselect_b32 s25, 0x70, 0
	s_sub_u32 s25, s97, s25
	s_cmpk_lt_u32 s25, 0x90
	s_cselect_b64 s[4:5], -1, 0
	v_readlane_b32 s23, v250, 1
	v_writelane_b32 v250, s4, 9
	s_load_dwordx8 s[64:71], s[34:35], 0x50
	s_mov_b32 s79, 0x20000
	v_writelane_b32 v250, s5, 10
	s_lshl_b32 s4, s25, 6
	s_mov_b32 s5, s37
	s_mov_b32 s2, s4
	s_lshl_b64 s[4:5], s[4:5], 2
	s_add_u32 s4, s74, s4
	s_addc_u32 s5, s75, s5
	s_add_u32 s26, s74, 0x1500000
	s_addc_u32 s27, s75, 0
	v_writelane_b32 v250, s2, 11
	s_add_u32 s28, s74, 0x1100000
	s_addc_u32 s29, s75, 0
	v_writelane_b32 v250, s3, 12
	v_writelane_b32 v250, s4, 13
	s_add_u32 s30, s74, 0x800000
	s_addc_u32 s31, s75, 0
	v_writelane_b32 v250, s5, 14
	s_lshl_b32 s2, s97, 9
	v_writelane_b32 v250, s2, 15
	s_lshl_b32 s2, s22, 9
	s_add_u32 s16, s74, 0x12000000
	s_addc_u32 s17, s75, 0
	s_cmpk_lt_i32 s97, 0xb00
	s_cselect_b64 s[4:5], -1, 0
	s_ashr_i32 s92, s97, 31
	v_writelane_b32 v250, s2, 16
	s_lshr_b32 s2, s92, 29
	v_writelane_b32 v250, s4, 17
	s_add_i32 s2, s97, s2
	s_ashr_i32 s96, s22, 31
	v_writelane_b32 v250, s5, 18
	s_ashr_i32 s4, s2, 3
	s_and_b32 s2, s2, -8
	s_sub_i32 s5, s97, s2
	s_add_u32 s2, s74, 0x2000
	v_writelane_b32 v250, s2, 19
	s_addc_u32 s2, s75, 0
	s_add_u32 s20, s74, 0x12b00000
	s_addc_u32 s21, s75, 0
	s_cmpk_lt_i32 s97, 0x200
	v_writelane_b32 v250, s2, 20
	s_cselect_b64 s[10:11], -1, 0
	v_writelane_b32 v250, s10, 21
	v_mbcnt_lo_u32_b32 v0, -1, 0
	s_mov_b32 s78, 0x1f200000
	v_writelane_b32 v250, s11, 22
	s_lshl_b32 s10, s5, 6
	s_cmpk_lt_i32 s97, 0x880
	s_cselect_b64 s[14:15], -1, 0
	v_writelane_b32 v250, s14, 23
	s_mov_b32 s76, s74
	s_brev_b32 s58, 16
	v_writelane_b32 v250, s15, 24
	s_add_u32 s14, s74, 0x200000
	s_addc_u32 s15, s75, 0
	v_writelane_b32 v250, s14, 25
	s_mov_b32 s59, s79
	s_mov_b32 s80, s72
	v_writelane_b32 v250, s15, 26
	s_waitcnt lgkmcnt(0)
	v_writelane_b32 v250, s40, 27
	s_add_u32 s14, s12, 0x3000
	s_addc_u32 s15, s13, 0
	v_writelane_b32 v250, s41, 28
	v_writelane_b32 v250, s42, 29
	v_writelane_b32 v250, s43, 30
	v_writelane_b32 v250, s14, 31
	s_cmpk_lt_i32 s97, 0x400
	v_mov_b32_e32 v97, 0
	v_writelane_b32 v250, s15, 32
	s_cselect_b64 s[14:15], -1, 0
	v_writelane_b32 v250, s14, 33
	s_lshl_b32 s11, s5, 7
	s_add_u32 s2, s74, 0x600000
	v_writelane_b32 v250, s15, 34
	v_writelane_b32 v250, s2, 35
	s_addc_u32 s2, s75, 0
	s_add_u32 s38, s74, 0x13000000
	s_addc_u32 s39, s75, 0
	s_add_u32 s14, s74, 0x17000000
	v_writelane_b32 v250, s2, 36
	s_addc_u32 s15, s75, 0
	v_writelane_b32 v250, s14, 37
	s_add_u32 s2, s74, 0x1b000000
	v_mov_b32_e32 v224, 1
	v_writelane_b32 v250, s15, 38
	v_writelane_b32 v250, s2, 39
	s_addc_u32 s2, s75, 0
	v_writelane_b32 v250, s2, 40
	s_add_u32 s2, s74, 0xb000000
	s_add_u32 s55, s74, 0xf000000
	s_addc_u32 s56, s75, 0
	v_writelane_b32 v250, s2, 41
	s_add_u32 s2, s74, 0x1f000000
	v_writelane_b32 v250, s2, 42
	s_addc_u32 s2, s75, 0
	v_writelane_b32 v250, s2, 43
	s_add_i32 s2, 0, 0x21000
	s_add_u32 s14, s74, 0x4000
	s_addc_u32 s15, s75, 0
	v_writelane_b32 v250, s14, 44
	v_lshl_add_u32 v223, v222, 2, s2
	v_mov_b32_e32 v225, 0x358637bd
	v_writelane_b32 v250, s15, 45
	s_add_u32 s14, s74, 0x3000
	s_addc_u32 s15, s75, 0
	v_writelane_b32 v250, s14, 46
	s_lshl_b32 s40, s22, 5
	v_mov_b32_e32 v226, 0x3ecc95a3
	v_writelane_b32 v250, s15, 47
	s_add_u32 s14, s74, 0x1000
	s_addc_u32 s15, s75, 0
	s_add_u32 s25, s74, 0x1900000
	v_writelane_b32 v250, s14, 48
	s_addc_u32 s33, s75, 0
	v_mbcnt_hi_u32_b32 v227, -1, v0
	v_writelane_b32 v250, s15, 49
	s_add_u32 s14, s12, 0x6060
	v_writelane_b32 v250, s12, 50
	s_addc_u32 s15, s13, 0
	s_add_u32 s36, s74, 0x1b00000
	v_writelane_b32 v250, s13, 51
	v_writelane_b32 v250, s14, 52
	s_addc_u32 s41, s75, 0
	s_add_u32 s12, s74, 0x8000
	v_writelane_b32 v250, s15, 53
	v_writelane_b32 v250, s12, 54
	s_addc_u32 s12, s75, 0
	s_add_u32 s42, s74, 0x2a00000
	s_addc_u32 s43, s75, 0
	s_add_u32 s44, s74, 0x1f00000
	s_addc_u32 s45, s75, 0
	v_writelane_b32 v250, s12, 55
	s_add_u32 s12, s74, 0x7000
	s_addc_u32 s13, s75, 0
	v_writelane_b32 v250, s12, 56
	v_mov_b32_e32 v228, 0xff800000
	v_mov_b32_e32 v229, 0x7f800000
	v_writelane_b32 v250, s13, 57
	s_add_u32 s12, s74, 0x6000
	s_addc_u32 s13, s75, 0
	v_writelane_b32 v250, s12, 58
	v_mov_b32_e32 v188, 0x3f317218
	v_mov_b32_e32 v230, 0x9000
	v_writelane_b32 v250, s13, 59
	s_add_u32 s12, s74, 0x5000
	v_writelane_b32 v250, s12, 60
	s_addc_u32 s12, s75, 0
	s_add_u32 s48, s74, 0x1d00000
	s_addc_u32 s49, s75, 0
	v_writelane_b32 v250, s12, 61
	s_add_u32 s12, s74, 0x104200
	s_addc_u32 s13, s75, 0
	v_writelane_b32 v250, s12, 62
	s_movk_i32 s93, 0x90
	s_mov_b32 s94, 0xbfb8aa3b
	v_writelane_b32 v250, s13, 63
	s_add_u32 s12, s74, 0x104400
	s_addc_u32 s13, s75, 0
	v_writelane_b32 v251, s12, 0
	s_mov_b32 s60, 0x3f2aaaab
	s_mov_b32 s61, 0x3f317218
	v_writelane_b32 v251, s13, 1
	s_add_u32 s12, s74, 0x104500
	s_addc_u32 s13, s75, 0
	v_writelane_b32 v251, s12, 2
	s_mov_b32 s95, 0x33800000
	s_nop 0
	v_writelane_b32 v251, s13, 3
	s_add_u32 s12, s74, 0x104600
	s_addc_u32 s13, s75, 0
	v_writelane_b32 v251, s12, 4
	s_nop 1
	v_writelane_b32 v251, s13, 5
	s_add_u32 s12, s74, 0x104700
	s_addc_u32 s13, s75, 0
	v_writelane_b32 v251, s12, 6
	s_nop 1
	v_writelane_b32 v251, s13, 7
	s_add_u32 s12, s74, 0x104800
	s_addc_u32 s13, s75, 0
	v_writelane_b32 v251, s12, 8
	s_nop 1
	v_writelane_b32 v251, s13, 9
	s_add_u32 s12, s74, 0x104900
	s_addc_u32 s13, s75, 0
	v_writelane_b32 v251, s12, 10
	s_nop 1
	v_writelane_b32 v251, s13, 11
	s_add_u32 s12, s74, 0x104a00
	s_addc_u32 s13, s75, 0
	v_writelane_b32 v251, s12, 12
	s_nop 1
	v_writelane_b32 v251, s13, 13
	s_add_u32 s12, s74, 0x104b00
	s_addc_u32 s13, s75, 0
	v_writelane_b32 v251, s12, 14
	s_nop 1
	v_writelane_b32 v251, s13, 15
	s_add_u32 s12, s74, 0x104c00
	s_addc_u32 s13, s75, 0
	v_writelane_b32 v251, s12, 16
	s_nop 1
	v_writelane_b32 v251, s13, 17
	s_add_u32 s12, s74, 0x104d00
	s_addc_u32 s13, s75, 0
	v_writelane_b32 v251, s12, 18
	s_nop 1
	v_writelane_b32 v251, s13, 19
	s_add_u32 s12, s74, 0x104e00
	s_addc_u32 s13, s75, 0
	v_writelane_b32 v251, s12, 20
	s_nop 1
	v_writelane_b32 v251, s13, 21
	s_add_u32 s12, s74, 0x104f00
	s_addc_u32 s13, s75, 0
	v_writelane_b32 v251, s12, 22
	s_nop 1
	v_writelane_b32 v251, s13, 23
	s_add_u32 s12, s74, 0x105000
	s_addc_u32 s13, s75, 0
	v_writelane_b32 v251, s12, 24
	s_nop 1
	v_writelane_b32 v251, s13, 25
	s_add_u32 s12, s74, 0x105100
	s_addc_u32 s13, s75, 0
	v_writelane_b32 v251, s12, 26
	s_nop 1
	v_writelane_b32 v251, s13, 27
	s_add_u32 s12, s74, 0x105200
	s_addc_u32 s13, s75, 0
	v_writelane_b32 v251, s12, 28
	s_nop 1
	v_writelane_b32 v251, s13, 29
	s_add_u32 s12, s74, 0x105300
	s_addc_u32 s13, s75, 0
	v_writelane_b32 v251, s12, 30
	s_cmp_eq_u32 s3, 15
	s_nop 0
	v_writelane_b32 v251, s13, 31
	s_cselect_b64 s[12:13], -1, 0
	v_writelane_b32 v251, s12, 32
	s_cmp_eq_u32 s3, 14
	s_nop 0
	v_writelane_b32 v251, s13, 33
	s_cselect_b64 s[12:13], -1, 0
	v_writelane_b32 v251, s12, 34
	s_cmp_eq_u32 s3, 13
	s_nop 0
	v_writelane_b32 v251, s13, 35
	s_cselect_b64 s[12:13], -1, 0
	v_writelane_b32 v251, s12, 36
	s_cmp_eq_u32 s3, 12
	s_nop 0
	v_writelane_b32 v251, s13, 37
	s_cselect_b64 s[12:13], -1, 0
	v_writelane_b32 v251, s12, 38
	s_cmp_eq_u32 s3, 11
	s_nop 0
	v_writelane_b32 v251, s13, 39
	s_cselect_b64 s[12:13], -1, 0
	v_writelane_b32 v251, s12, 40
	s_cmp_eq_u32 s3, 10
	s_nop 0
	v_writelane_b32 v251, s13, 41
	s_cselect_b64 s[12:13], -1, 0
	v_writelane_b32 v251, s12, 42
	s_cmp_eq_u32 s3, 9
	s_nop 0
	v_writelane_b32 v251, s13, 43
	s_cselect_b64 s[12:13], -1, 0
	v_writelane_b32 v251, s12, 44
	s_cmp_eq_u32 s3, 8
	s_nop 0
	v_writelane_b32 v251, s13, 45
	s_cselect_b64 s[12:13], -1, 0
	v_writelane_b32 v251, s12, 46
	s_cmp_eq_u32 s3, 7
	s_nop 0
	v_writelane_b32 v251, s13, 47
	s_cselect_b64 s[12:13], -1, 0
	v_writelane_b32 v251, s12, 48
	s_cmp_eq_u32 s3, 6
	s_nop 0
	v_writelane_b32 v251, s13, 49
	s_cselect_b64 s[12:13], -1, 0
	v_writelane_b32 v251, s12, 50
	s_cmp_eq_u32 s3, 5
	s_nop 0
	v_writelane_b32 v251, s13, 51
	s_cselect_b64 s[12:13], -1, 0
	v_writelane_b32 v251, s12, 52
	s_cmp_eq_u32 s3, 4
	s_nop 0
	v_writelane_b32 v251, s13, 53
	s_cselect_b64 s[12:13], -1, 0
	v_writelane_b32 v251, s12, 54
	s_cmp_eq_u32 s3, 3
	s_nop 0
	v_writelane_b32 v251, s13, 55
	s_cselect_b64 s[12:13], -1, 0
	v_writelane_b32 v251, s12, 56
	s_cmp_eq_u32 s3, 2
	s_nop 0
	v_writelane_b32 v251, s13, 57
	s_cselect_b64 s[12:13], -1, 0
	v_writelane_b32 v251, s12, 58
	s_cmp_eq_u32 s3, 1
	s_nop 0
	v_writelane_b32 v251, s13, 59
	s_cselect_b64 s[12:13], -1, 0
	v_writelane_b32 v251, s12, 60
	s_cmp_eq_u32 s3, 0
	s_nop 0
	v_writelane_b32 v251, s13, 61
	s_cselect_b64 s[12:13], -1, 0
	s_lshl_b32 s3, s3, 8
	s_add_u32 s0, s0, s3
	v_writelane_b32 v251, s12, 62
	s_addc_u32 s1, s1, 0
	s_nop 0
	v_writelane_b32 v251, s13, 63
	s_add_u32 s12, s0, 0x1400
	s_addc_u32 s13, s1, 0
	v_writelane_b32 v252, s12, 0
	s_add_u32 s0, s0, 0x2400
	s_addc_u32 s1, s1, 0
	v_writelane_b32 v252, s13, 1
	v_writelane_b32 v252, s0, 2
	s_nop 1
	v_writelane_b32 v252, s1, 3
	s_add_u32 s0, s74, 0x107400
	s_addc_u32 s1, s75, 0
	v_writelane_b32 v252, s0, 4
	s_nop 1
	v_writelane_b32 v252, s1, 5
	s_add_u32 s0, s74, 0x107500
	s_addc_u32 s1, s75, 0
	v_writelane_b32 v252, s0, 6
	s_cmp_lt_i32 s5, 0
	s_nop 0
	v_writelane_b32 v252, s1, 7
	s_mul_i32 s0, s5, 0x41
	s_cselect_b32 s3, s0, s10
	s_mul_i32 s0, s5, 0x81
	s_cselect_b32 s14, s0, s11
	s_movk_i32 s0, 0x161
	s_cselect_b32 s0, s0, 0x160
	s_mul_i32 s0, s5, s0
	s_movk_i32 s1, 0x111
	s_cselect_b32 s15, s1, 0x110
	s_add_i32 s0, s0, s4
	s_mul_hi_i32 s1, s0, 0x2e8ba2e9
	s_lshr_b32 s10, s1, 31
	s_ashr_i32 s1, s1, 5
	s_add_i32 s1, s1, s10
	s_mul_i32 s10, s1, 0xb0
	s_sub_i32 s0, s0, s10
	s_bfe_u32 s10, s0, 0x3001c
	s_add_i32 s10, s0, s10
	s_and_b32 s11, s10, 0xfff8
	s_sub_i32 s0, s0, s11
	s_lshl_b32 s1, s1, 3
	s_sext_i32_i16 s10, s10
	s_sext_i32_i16 s0, s0
	s_add_i32 s12, s1, s0
	s_ashr_i32 s0, s10, 3
	v_writelane_b32 v252, s0, 8
	s_lshr_b32 s0, s10, 3
	s_bfe_i64 s[0:1], s[0:1], 0x100000
	s_lshl_b64 s[10:11], s[0:1], 19
	s_mov_b32 s0, s12
	s_ashr_i32 s13, s12, 31
	v_writelane_b32 v252, s0, 9
	s_mul_i32 s5, s5, s15
	s_nop 0
	v_writelane_b32 v252, s1, 10
	s_lshl_b64 s[0:1], s[12:13], 19
	s_add_u32 s12, s16, s10
	s_addc_u32 s13, s17, s11
	v_writelane_b32 v252, s16, 11
	s_add_u32 s16, s12, 0x40000
	v_writelane_b32 v252, s17, 12
	s_addc_u32 s17, s13, 0
	v_writelane_b32 v252, s16, 13
	s_nop 1
	v_writelane_b32 v252, s17, 14
	s_add_u32 s16, s6, s0
	s_addc_u32 s17, s7, s1
	s_add_u32 s18, s16, 0x40000
	v_writelane_b32 v252, s16, 15
	s_addc_u32 s19, s17, 0
	s_nop 0
	v_writelane_b32 v252, s17, 16
	v_writelane_b32 v252, s18, 17
	s_add_u32 s16, s12, 0x40080
	s_nop 0
	v_writelane_b32 v252, s19, 18
	v_writelane_b32 v252, s12, 19
	s_addc_u32 s17, s13, 0
	s_add_i32 s3, s3, s4
	v_writelane_b32 v252, s13, 20
	s_ashr_i32 s12, s3, 31
	s_lshr_b32 s12, s12, 27
	s_add_i32 s12, s3, s12
	s_and_b32 s13, s12, 0xffe0
	s_sub_i32 s3, s3, s13
	s_bfe_i32 s13, s3, 0x80000
	s_bfe_u32 s13, s13, 0x3000c
	v_writelane_b32 v252, s16, 21
	s_add_i32 s13, s3, s13
	s_ashr_i32 s12, s12, 5
	v_writelane_b32 v252, s17, 22
	s_and_b32 s16, s13, 0xf8
	s_sub_i32 s3, s3, s16
	s_bfe_i32 s13, s13, 0x80000
	s_lshl_b32 s12, s12, 3
	s_sext_i32_i16 s13, s13
	s_sext_i32_i8 s3, s3
	s_add_i32 s50, s12, s3
	s_ashr_i32 s16, s13, 3
	s_lshr_b32 s12, s13, 3
	s_ashr_i32 s51, s50, 31
	s_bfe_i64 s[18:19], s[12:13], 0x100000
	v_writelane_b32 v252, s16, 23
	s_mul_i32 s13, s16, 0x160000
	s_mul_hi_i32 s3, s16, 0x160000
	v_writelane_b32 v252, s20, 24
	s_add_u32 s20, s20, s13
	v_writelane_b32 v252, s21, 25
	s_addc_u32 s21, s21, s3
	s_add_u32 s16, s20, 0xb0000
	s_addc_u32 s17, s21, 0
	v_writelane_b32 v252, s16, 26
	s_mul_hi_i32 s12, s50, 0x160000
	s_nop 0
	v_writelane_b32 v252, s17, 27
	s_mul_i32 s16, s50, 0x160000
	s_add_u32 s16, s8, s16
	s_addc_u32 s17, s9, s12
	s_add_u32 s52, s16, 0xb0000
	v_writelane_b32 v252, s16, 28
	s_addc_u32 s53, s17, 0
	s_nop 0
	v_writelane_b32 v252, s17, 29
	v_writelane_b32 v252, s52, 30
	s_add_u32 s16, s20, 0xb0080
	s_nop 0
	v_writelane_b32 v252, s53, 31
	v_writelane_b32 v252, s20, 32
	s_addc_u32 s17, s21, 0
	s_add_i32 s5, s5, s4
	s_mul_hi_i32 s12, s5, 0x78787879
	s_lshr_b32 s15, s12, 31
	s_ashr_i32 s12, s12, 6
	s_add_i32 s12, s12, s15
	s_mul_i32 s15, s12, 0x88
	s_sub_i32 s5, s5, s15
	v_writelane_b32 v252, s21, 33
	s_bfe_u32 s15, s5, 0x3001c
	v_writelane_b32 v252, s16, 34
	s_add_i32 s15, s5, s15
	s_lshl_b32 s12, s12, 3
	v_writelane_b32 v252, s17, 35
	s_and_b32 s16, s15, 0xfff8
	s_sub_i32 s5, s5, s16
	s_add_i32 s16, s14, s4
	s_ashr_i32 s17, s16, 31
	s_lshr_b32 s4, s17, 22
	s_add_i32 s4, s16, s4
	s_and_b32 s14, s4, 0xfc00
	s_sub_i32 s14, s16, s14
	s_sext_i32_i16 s20, s14
	s_bfe_u32 s20, s20, 0x3001c
	s_add_i32 s20, s14, s20
	s_and_b32 s21, s20, 0xfff8
	s_sub_i32 s14, s14, s21
	s_sext_i32_i16 s5, s5
	s_ashr_i32 s4, s4, 10
	s_add_i32 s52, s12, s5
	s_lshl_b32 s4, s4, 3
	s_sext_i32_i16 s5, s20
	s_sext_i32_i16 s12, s14
	s_sext_i32_i16 s15, s15
	s_add_i32 s20, s4, s12
	s_ashr_i32 s4, s5, 3
	v_writelane_b32 v252, s4, 36
	s_ashr_i32 s12, s15, 3
	s_lshr_b32 s4, s5, 3
	v_writelane_b32 v252, s12, 37
	s_mov_b32 s14, s20
	s_ashr_i32 s21, s20, 31
	s_bfe_i64 s[4:5], s[4:5], 0x100000
	s_lshr_b32 s12, s15, 3
	v_writelane_b32 v252, s14, 38
	s_lshl_b64 s[4:5], s[4:5], 19
	s_nop 0
	v_writelane_b32 v252, s15, 39
	s_lshl_b64 s[14:15], s[20:21], 19
	s_add_u32 s4, s6, s4
	s_addc_u32 s5, s7, s5
	s_add_u32 s20, s4, 0x40000
	s_addc_u32 s21, s5, 0
	v_writelane_b32 v252, s20, 40
	s_add_u32 s14, s28, s14
	s_nop 0
	v_writelane_b32 v252, s21, 41
	v_writelane_b32 v252, s28, 42
	s_addc_u32 s15, s29, s15
	s_add_u32 s20, s14, 0x40000
	v_writelane_b32 v252, s29, 43
	v_writelane_b32 v252, s14, 44
	s_addc_u32 s21, s15, 0
	s_nop 0
	v_writelane_b32 v252, s15, 45
	v_writelane_b32 v252, s20, 46
	s_add_u32 s14, s4, 0x40080
	s_nop 0
	v_writelane_b32 v252, s21, 47
	v_writelane_b32 v252, s4, 48
	s_addc_u32 s15, s5, 0
	s_lshl_b64 s[20:21], s[18:19], 19
	v_writelane_b32 v252, s5, 49
	v_writelane_b32 v252, s14, 50
	s_mov_b32 s4, s50
	s_lshl_b64 s[18:19], s[50:51], 19
	v_writelane_b32 v252, s15, 51
	v_writelane_b32 v252, s4, 52
	s_nop 1
	v_writelane_b32 v252, s5, 53
	s_add_u32 s4, s25, s20
	s_addc_u32 s5, s33, s21
	v_writelane_b32 v252, s25, 54
	s_add_u32 s14, s4, 0x40000
	v_writelane_b32 v252, s33, 55
	s_addc_u32 s15, s5, 0
	v_writelane_b32 v252, s14, 56
	s_mov_b32 s25, 0x7f800000
	s_nop 0
	v_writelane_b32 v252, s15, 57
	s_add_u32 s14, s55, s18
	v_writelane_b32 v252, s55, 58
	s_addc_u32 s15, s56, s19
	v_writelane_b32 v252, s56, 59
	s_add_u32 s28, s14, 0x40000
	v_writelane_b32 v252, s14, 60
	s_addc_u32 s29, s15, 0
	s_mov_b32 s56, s46
	v_writelane_b32 v252, s15, 61
	s_add_u32 s14, s4, 0x40080
	v_writelane_b32 v253, s4, 0
	s_addc_u32 s15, s5, 0
	v_writelane_b32 v252, s28, 62
	v_writelane_b32 v253, s5, 1
	s_lshr_b32 s4, s17, 26
	s_add_i32 s4, s16, s4
	s_and_b32 s5, s4, 0xffc0
	v_writelane_b32 v253, s14, 2
	s_sub_i32 s5, s16, s5
	s_ashr_i32 s4, s4, 6
	v_writelane_b32 v253, s15, 3
	s_bfe_i32 s14, s5, 0x80000
	s_bfe_u32 s14, s14, 0x3000c
	s_add_i32 s14, s5, s14
	s_and_b32 s15, s14, 0xf8
	s_sub_i32 s5, s5, s15
	s_bfe_i32 s14, s14, 0x80000
	s_lshl_b32 s4, s4, 3
	s_sext_i32_i16 s14, s14
	s_sext_i32_i8 s5, s5
	s_add_i32 s16, s4, s5
	s_ashr_i32 s4, s14, 3
	v_writelane_b32 v253, s4, 4
	s_lshr_b32 s4, s14, 3
	s_mov_b32 s14, s16
	s_ashr_i32 s17, s16, 31
	s_bfe_i64 s[4:5], s[4:5], 0x100000
	v_writelane_b32 v253, s14, 5
	s_lshl_b64 s[4:5], s[4:5], 19
	v_writelane_b32 v252, s29, 63
	v_writelane_b32 v253, s15, 6
	s_lshl_b64 s[14:15], s[16:17], 19
	s_add_u32 s4, s26, s4
	v_writelane_b32 v253, s26, 7
	s_addc_u32 s5, s27, s5
	s_add_u32 s16, s4, 0x40000
	v_writelane_b32 v253, s27, 8
	s_addc_u32 s17, s5, 0
	v_writelane_b32 v253, s16, 9
	s_add_u32 s14, s6, s14
	s_addc_u32 s15, s7, s15
	v_writelane_b32 v253, s17, 10
	s_add_u32 s16, s14, 0x40000
	v_writelane_b32 v253, s14, 11
	s_addc_u32 s17, s15, 0
	s_mov_b32 s28, 0xc2ce8ed0
	v_writelane_b32 v253, s15, 12
	v_writelane_b32 v253, s16, 13
	s_add_u32 s14, s4, 0x40080
	s_mov_b32 s29, 0x42b17218
	v_writelane_b32 v253, s17, 14
	v_writelane_b32 v253, s4, 15
	s_addc_u32 s15, s5, 0
	s_mov_b64 s[26:27], 0x80
	v_writelane_b32 v253, s5, 16
	v_writelane_b32 v253, s14, 17
	s_add_u32 s4, s36, s20
	s_addc_u32 s5, s41, s21
	v_writelane_b32 v253, s15, 18
	v_writelane_b32 v253, s36, 19
	s_add_u32 s14, s4, 0x40000
	v_writelane_b32 v253, s41, 20
	s_addc_u32 s15, s5, 0
	v_writelane_b32 v253, s14, 21
	s_mov_b32 s36, 0
	s_nop 0
	v_writelane_b32 v253, s15, 22
	s_add_u32 s14, s38, s18
	s_addc_u32 s15, s39, s19
	s_add_u32 s16, s14, 0x40000
	v_writelane_b32 v253, s14, 23
	s_addc_u32 s17, s15, 0
	s_nop 0
	v_writelane_b32 v253, s15, 24
	v_writelane_b32 v253, s16, 25
	s_add_u32 s14, s4, 0x40080
	s_nop 0
	v_writelane_b32 v253, s17, 26
	v_writelane_b32 v253, s4, 27
	s_addc_u32 s15, s5, 0
	s_nop 0
	v_writelane_b32 v253, s5, 28
	v_writelane_b32 v253, s14, 29
	s_add_u32 s4, s42, s13
	s_addc_u32 s5, s43, s3
	v_writelane_b32 v253, s15, 30
	v_writelane_b32 v253, s42, 31
	s_add_u32 s14, s4, 0xb0000
	v_writelane_b32 v253, s43, 32
	s_addc_u32 s15, s5, 0
	v_writelane_b32 v253, s14, 33
	s_load_dwordx2 s[2:3], s[34:35], 0x70
	s_nop 0
	v_writelane_b32 v253, s15, 34
	s_add_u32 s14, s4, 0xb0080
	v_writelane_b32 v253, s4, 35
	s_addc_u32 s15, s5, 0
	s_nop 0
	v_writelane_b32 v253, s5, 36
	v_writelane_b32 v253, s14, 37
	s_add_u32 s4, s44, s10
	s_addc_u32 s5, s45, s11
	v_writelane_b32 v253, s15, 38
	v_writelane_b32 v253, s44, 39
	s_add_u32 s10, s4, 0x40000
	v_writelane_b32 v253, s45, 40
	s_addc_u32 s11, s5, 0
	v_writelane_b32 v253, s10, 41
	s_add_u32 s0, s38, s0
	s_nop 0
	v_writelane_b32 v253, s11, 42
	v_writelane_b32 v253, s38, 43
	s_addc_u32 s1, s39, s1
	s_add_u32 s10, s0, 0x40000
	v_writelane_b32 v253, s39, 44
	v_writelane_b32 v253, s0, 45
	s_addc_u32 s11, s1, 0
	s_mov_b32 s39, 0xb2a5705f
	v_writelane_b32 v253, s1, 46
	v_writelane_b32 v253, s10, 47
	s_add_u32 s0, s4, 0x40080
	s_mov_b32 s38, 0x3c800000
	v_writelane_b32 v253, s11, 48
	v_writelane_b32 v253, s4, 49
	s_addc_u32 s1, s5, 0
	s_nop 0
	v_writelane_b32 v253, s5, 50
	v_writelane_b32 v253, s0, 51
	s_nop 1
	v_writelane_b32 v253, s1, 52
	s_add_u32 s0, s48, s20
	s_addc_u32 s1, s49, s21
	v_writelane_b32 v253, s48, 53
	s_add_u32 s4, s0, 0x40000
	v_writelane_b32 v253, s49, 54
	s_addc_u32 s5, s1, 0
	v_writelane_b32 v253, s4, 55
	s_nop 1
	v_writelane_b32 v253, s5, 56
	s_add_u32 s4, s6, s18
	s_addc_u32 s5, s7, s19
	s_add_u32 s10, s4, 0x40000
	v_writelane_b32 v253, s4, 57
	s_addc_u32 s11, s5, 0
	s_nop 0
	v_writelane_b32 v253, s5, 58
	v_writelane_b32 v253, s10, 59
	s_add_u32 s4, s0, 0x40080
	s_nop 0
	v_writelane_b32 v253, s11, 60
	v_writelane_b32 v253, s0, 61
	s_addc_u32 s5, s1, 0
	s_ashr_i32 s53, s52, 31
	v_writelane_b32 v253, s1, 62
	v_writelane_b32 v253, s4, 63
	s_bfe_i64 s[0:1], s[12:13], 0x100000
	s_lshl_b64 s[0:1], s[0:1], 19
	v_writelane_b32 v254, s5, 0
	s_mov_b32 s4, s52
	v_writelane_b32 v254, s4, 1
	s_load_dwordx8 s[12:19], s[34:35], 0x8
	s_nop 0
	v_writelane_b32 v254, s5, 2
	s_lshl_b64 s[4:5], s[52:53], 19
	s_add_u32 s10, s30, s0
	v_writelane_b32 v254, s30, 3
	s_addc_u32 s11, s31, s1
	s_add_u32 s0, s10, 0x40000
	v_writelane_b32 v254, s31, 4
	s_addc_u32 s1, s11, 0
	v_writelane_b32 v254, s0, 5
	s_add_u32 s4, s6, s4
	s_addc_u32 s5, s7, s5
	v_writelane_b32 v254, s1, 6
	s_load_dword s1, s[34:35], 0xf8
	s_mul_i32 s0, s23, s22
	s_mov_b32 s30, 0x800000
	s_mov_b32 s23, 0xc2b17218
	s_waitcnt lgkmcnt(0)
	s_mul_i32 s0, s0, s1
	v_writelane_b32 v254, s0, 7
	s_add_u32 s0, s4, 0x40000
	v_writelane_b32 v254, s4, 8
	s_addc_u32 s1, s5, 0
	s_nop 0
	v_writelane_b32 v254, s5, 9
	v_writelane_b32 v254, s0, 10
	s_nop 1
	v_writelane_b32 v254, s1, 11
	s_add_u32 s0, s10, 0x40080
	v_writelane_b32 v254, s10, 12
	s_addc_u32 s1, s11, 0
	s_ashr_i32 s55, s54, 31
	v_writelane_b32 v254, s11, 13
	v_writelane_b32 v254, s0, 14
	s_ashr_i32 s41, s40, 31
	s_lshl_b32 s63, s22, 4
	v_writelane_b32 v254, s1, 15
	s_movk_i32 s0, 0x80
	v_cmp_gt_u32_e64 s[0:1], s0, v222
	s_add_i32 s10, 0, 0x21200
	s_nop 0
	v_writelane_b32 v254, s0, 16
	s_nop 1
	v_writelane_b32 v254, s1, 17
	s_mul_i32 s0, s22, 24
	v_writelane_b32 v254, s0, 18
	v_writelane_b32 v254, s24, 19
	s_add_i32 s0, s24, 0xffffe780
	v_writelane_b32 v254, s0, 20
	s_lshl_b32 s0, s97, 4
	v_writelane_b32 v254, s0, 21
	s_lshl_b32 s0, s97, 12
	v_writelane_b32 v254, s0, 22
	s_lshl_b32 s0, s22, 12
	v_writelane_b32 v254, s0, 23
	s_add_i32 s0, 0, 0x23000
	v_writelane_b32 v254, s0, 24
	s_add_i32 s0, 0, 0x9180
	v_writelane_b32 v254, s0, 25
	s_add_i32 s0, 0, 0x6c00
	v_writelane_b32 v254, s0, 26
	s_add_i32 s0, 0, 0x23040
	v_writelane_b32 v254, s0, 27
	s_add_i32 s0, 0, 0x23044
	v_writelane_b32 v254, s0, 28
	s_movk_i32 s1, 0x110
	s_mov_b32 s0, 0
	v_writelane_b32 v254, s0, 29
	v_writelane_b32 v254, s2, 30
	s_mov_b32 s0, s40
	s_mov_b32 s22, 0x42ce8ed0
	v_writelane_b32 v254, s3, 31
	s_lshl_b64 s[2:3], s[54:55], 13
	v_writelane_b32 v254, s2, 32
	s_mov_b32 s24, 0x3db504f3
	s_nop 0
	v_writelane_b32 v254, s3, 33
	s_lshl_b64 s[2:3], s[40:41], 11
	v_writelane_b32 v254, s2, 34
	s_nop 1
	v_writelane_b32 v254, s3, 35
	v_writelane_b32 v254, s0, 36
	s_lshl_b64 s[2:3], s[40:41], 12
	s_nop 0
	v_writelane_b32 v254, s1, 37
	v_writelane_b32 v254, s2, 38
	s_mov_b32 s0, 0x3fb8aa3b
	s_nop 0
	v_writelane_b32 v254, s3, 39
	v_writelane_b32 v254, s12, 40
	s_mov_b32 s2, s54
	s_nop 0
	v_writelane_b32 v254, s13, 41
	v_writelane_b32 v254, s14, 42
	v_writelane_b32 v254, s15, 43
	v_writelane_b32 v254, s16, 44
	v_writelane_b32 v254, s17, 45
	v_writelane_b32 v254, s18, 46
	v_writelane_b32 v254, s19, 47
	v_writelane_b32 v254, s97, 48
	v_writelane_b32 v254, s2, 49
	s_nop 1
	v_writelane_b32 v254, s3, 50
	v_writelane_b32 v254, s92, 51
	v_writelane_b32 v254, s96, 52
	v_writelane_b32 v254, s63, 53
	v_writelane_b32 v254, s46, 54
	s_nop 1
	v_writelane_b32 v254, s47, 55
	s_branch .LBB0_22

.LBB0_302:
	v_mad_i64_i32 v[0:1], s[48:49], s2, v230, v[64:65]
	s_mov_b32 s50, 0x9000
	s_mov_b32 s51, 0
	v_mov_b32_e32 v2, s3
	global_load_dword v100, v[0:1], off
	v_lshl_add_u64 v[0:1], v[0:1], 0, s[50:51]
	global_load_dword v101, v[0:1], off
	v_lshl_add_u64 v[0:1], v[0:1], 0, s[50:51]
	global_load_dword v102, v[0:1], off
	v_lshl_add_u64 v[0:1], v[0:1], 0, s[50:51]
	global_load_dword v103, v[0:1], off
	v_lshl_add_u64 v[0:1], v[0:1], 0, s[50:51]
	global_load_dword v104, v[0:1], off
	v_lshl_add_u64 v[0:1], v[0:1], 0, s[50:51]
	global_load_dword v105, v[0:1], off
	v_lshl_add_u64 v[0:1], v[0:1], 0, s[50:51]
	global_load_dword v106, v[0:1], off
	v_lshl_add_u64 v[0:1], v[0:1], 0, s[50:51]
	global_load_dword v107, v[0:1], off
	v_lshl_add_u64 v[0:1], v[0:1], 0, s[50:51]
	global_load_dword v108, v[0:1], off
	v_lshl_add_u64 v[0:1], v[0:1], 0, s[50:51]
	global_load_dword v109, v[0:1], off
	v_lshl_add_u64 v[0:1], v[0:1], 0, s[50:51]
	global_load_dword v110, v[0:1], off
	v_lshl_add_u64 v[0:1], v[0:1], 0, s[50:51]
	global_load_dword v111, v[0:1], off
	v_lshl_add_u64 v[0:1], v[0:1], 0, s[50:51]
	global_load_dword v112, v[0:1], off
	v_lshl_add_u64 v[0:1], v[0:1], 0, s[50:51]
	global_load_dword v113, v[0:1], off
	v_lshl_add_u64 v[0:1], v[0:1], 0, s[50:51]
	global_load_dword v114, v[0:1], off
	v_lshl_add_u64 v[0:1], v[0:1], 0, s[50:51]
	global_load_dword v115, v[0:1], off
	v_lshl_add_u64 v[0:1], v[0:1], 0, s[50:51]
	global_load_dword v116, v[0:1], off
	v_lshl_add_u64 v[0:1], v[0:1], 0, s[50:51]
	global_load_dword v117, v[0:1], off
	v_lshl_add_u64 v[0:1], v[0:1], 0, s[50:51]
	global_load_dword v118, v[0:1], off
	v_lshl_add_u64 v[0:1], v[0:1], 0, s[50:51]
	global_load_dword v119, v[0:1], off
	v_lshl_add_u64 v[0:1], v[0:1], 0, s[50:51]
	global_load_dword v120, v[0:1], off
	v_lshl_add_u64 v[0:1], v[0:1], 0, s[50:51]
	global_load_dword v121, v[0:1], off
	v_lshl_add_u64 v[0:1], v[0:1], 0, s[50:51]
	global_load_dword v122, v[0:1], off
	v_lshl_add_u64 v[0:1], v[0:1], 0, s[50:51]
	global_load_dword v123, v[0:1], off
	v_lshl_add_u64 v[0:1], v[0:1], 0, s[50:51]
	global_load_dword v124, v[0:1], off
	v_lshl_add_u64 v[0:1], v[0:1], 0, s[50:51]
	global_load_dword v125, v[0:1], off
	v_lshl_add_u64 v[0:1], v[0:1], 0, s[50:51]
	global_load_dword v126, v[0:1], off
	v_lshl_add_u64 v[0:1], v[0:1], 0, s[50:51]
	global_load_dword v127, v[0:1], off
	v_lshl_add_u64 v[0:1], v[0:1], 0, s[50:51]
	global_load_dword v128, v[0:1], off
	v_lshl_add_u64 v[0:1], v[0:1], 0, s[50:51]
	global_load_dword v129, v[0:1], off
	v_lshl_add_u64 v[0:1], v[0:1], 0, s[50:51]
	global_load_dword v130, v[0:1], off
	v_lshl_add_u64 v[0:1], v[0:1], 0, s[50:51]
	global_load_dword v131, v[0:1], off
	v_lshl_add_u64 v[0:1], v[0:1], 0, s[50:51]
	global_load_dword v132, v[0:1], off
	v_lshl_add_u64 v[0:1], v[0:1], 0, s[50:51]
	global_load_dword v133, v[0:1], off
	v_lshl_add_u64 v[0:1], v[0:1], 0, s[50:51]
	global_load_dword v134, v[0:1], off
	v_lshl_add_u64 v[0:1], v[0:1], 0, s[50:51]
	global_load_dword v135, v[0:1], off
	v_lshl_add_u64 v[0:1], v[0:1], 0, s[50:51]
	global_load_dword v136, v[0:1], off
	v_lshl_add_u64 v[0:1], v[0:1], 0, s[50:51]
	global_load_dword v137, v[0:1], off
	v_lshl_add_u64 v[0:1], v[0:1], 0, s[50:51]
	global_load_dword v138, v[0:1], off
	v_lshl_add_u64 v[0:1], v[0:1], 0, s[50:51]
	global_load_dword v139, v[0:1], off
	v_lshl_add_u64 v[0:1], v[0:1], 0, s[50:51]
	global_load_dword v140, v[0:1], off
	v_lshl_add_u64 v[0:1], v[0:1], 0, s[50:51]
	global_load_dword v141, v[0:1], off
	v_lshl_add_u64 v[0:1], v[0:1], 0, s[50:51]
	global_load_dword v142, v[0:1], off
	v_lshl_add_u64 v[0:1], v[0:1], 0, s[50:51]
	global_load_dword v143, v[0:1], off
	v_lshl_add_u64 v[0:1], v[0:1], 0, s[50:51]
	global_load_dword v144, v[0:1], off
	v_lshl_add_u64 v[0:1], v[0:1], 0, s[50:51]
	global_load_dword v145, v[0:1], off
	v_lshl_add_u64 v[0:1], v[0:1], 0, s[50:51]
	global_load_dword v146, v[0:1], off
	v_lshl_add_u64 v[0:1], v[0:1], 0, s[50:51]
	global_load_dword v147, v[0:1], off
	v_lshl_add_u64 v[0:1], v[0:1], 0, s[50:51]
	ds_read_b128 v[148:151], v2 offset:0
	ds_read_b128 v[152:155], v2 offset:4096
	ds_read_b128 v[156:159], v2 offset:8192
	ds_read_b128 v[160:163], v2 offset:12288
	ds_read_b128 v[164:167], v2 offset:16384
	ds_read_b128 v[168:171], v2 offset:20480
	ds_read_b128 v[172:175], v2 offset:24576
	ds_read_b128 v[176:179], v2 offset:28672
	s_waitcnt vmcnt(32)
	ds_read_b128 v[28:31], v2 offset:32768
	ds_read_b128 v[32:35], v2 offset:36864
	ds_read_b128 v[36:39], v2 offset:40960
	ds_read_b128 v[40:43], v2 offset:45056
	s_waitcnt lgkmcnt(8)
	v_fmac_f32_e32 v12, v100, v148
	v_fmac_f32_e32 v13, v100, v152
	v_fmac_f32_e32 v14, v100, v156
	v_fmac_f32_e32 v15, v100, v160
	v_fmac_f32_e32 v12, v101, v149
	v_fmac_f32_e32 v13, v101, v153
	v_fmac_f32_e32 v14, v101, v157
	v_fmac_f32_e32 v15, v101, v161
	v_fmac_f32_e32 v12, v102, v150
	v_fmac_f32_e32 v13, v102, v154
	v_fmac_f32_e32 v14, v102, v158
	v_fmac_f32_e32 v15, v102, v162
	v_fmac_f32_e32 v12, v103, v151
	v_fmac_f32_e32 v13, v103, v155
	v_fmac_f32_e32 v14, v103, v159
	v_fmac_f32_e32 v15, v103, v163
	ds_read_b128 v[148:151], v2 offset:49152
	ds_read_b128 v[152:155], v2 offset:53248
	ds_read_b128 v[156:159], v2 offset:57344
	ds_read_b128 v[160:163], v2 offset:61440
	s_waitcnt lgkmcnt(8)
	v_fmac_f32_e32 v16, v100, v164
	v_fmac_f32_e32 v17, v100, v168
	v_fmac_f32_e32 v20, v100, v172
	v_fmac_f32_e32 v21, v100, v176
	v_fmac_f32_e32 v16, v101, v165
	v_fmac_f32_e32 v17, v101, v169
	v_fmac_f32_e32 v20, v101, v173
	v_fmac_f32_e32 v21, v101, v177
	v_fmac_f32_e32 v16, v102, v166
	v_fmac_f32_e32 v17, v102, v170
	v_fmac_f32_e32 v20, v102, v174
	v_fmac_f32_e32 v21, v102, v178
	v_fmac_f32_e32 v16, v103, v167
	v_fmac_f32_e32 v17, v103, v171
	v_fmac_f32_e32 v20, v103, v175
	v_fmac_f32_e32 v21, v103, v179
	ds_read_b128 v[164:167], v2 offset:16
	ds_read_b128 v[168:171], v2 offset:4112
	ds_read_b128 v[172:175], v2 offset:8208
	ds_read_b128 v[176:179], v2 offset:12304
	s_waitcnt lgkmcnt(8)
	v_fmac_f32_e32 v24, v100, v28
	v_fmac_f32_e32 v25, v100, v32
	v_fmac_f32_e32 v18, v100, v36
	v_fmac_f32_e32 v19, v100, v40
	v_fmac_f32_e32 v24, v101, v29
	v_fmac_f32_e32 v25, v101, v33
	v_fmac_f32_e32 v18, v101, v37
	v_fmac_f32_e32 v19, v101, v41
	v_fmac_f32_e32 v24, v102, v30
	v_fmac_f32_e32 v25, v102, v34
	v_fmac_f32_e32 v18, v102, v38
	v_fmac_f32_e32 v19, v102, v42
	v_fmac_f32_e32 v24, v103, v31
	v_fmac_f32_e32 v25, v103, v35
	v_fmac_f32_e32 v18, v103, v39
	v_fmac_f32_e32 v19, v103, v43
	ds_read_b128 v[28:31], v2 offset:16400
	ds_read_b128 v[32:35], v2 offset:20496
	ds_read_b128 v[36:39], v2 offset:24592
	ds_read_b128 v[40:43], v2 offset:28688
	s_waitcnt lgkmcnt(8)
	v_fmac_f32_e32 v22, v100, v148
	v_fmac_f32_e32 v23, v100, v152
	v_fmac_f32_e32 v26, v100, v156
	v_fmac_f32_e32 v27, v100, v160
	v_fmac_f32_e32 v22, v101, v149
	v_fmac_f32_e32 v23, v101, v153
	v_fmac_f32_e32 v26, v101, v157
	v_fmac_f32_e32 v27, v101, v161
	v_fmac_f32_e32 v22, v102, v150
	v_fmac_f32_e32 v23, v102, v154
	v_fmac_f32_e32 v26, v102, v158
	v_fmac_f32_e32 v27, v102, v162
	v_fmac_f32_e32 v22, v103, v151
	v_fmac_f32_e32 v23, v103, v155
	v_fmac_f32_e32 v26, v103, v159
	v_fmac_f32_e32 v27, v103, v163
	ds_read_b128 v[148:151], v2 offset:32784
	ds_read_b128 v[152:155], v2 offset:36880
	ds_read_b128 v[156:159], v2 offset:40976
	ds_read_b128 v[160:163], v2 offset:45072
	s_waitcnt lgkmcnt(8)
	v_fmac_f32_e32 v12, v104, v164
	v_fmac_f32_e32 v13, v104, v168
	v_fmac_f32_e32 v14, v104, v172
	v_fmac_f32_e32 v15, v104, v176
	v_fmac_f32_e32 v12, v105, v165
	v_fmac_f32_e32 v13, v105, v169
	v_fmac_f32_e32 v14, v105, v173
	v_fmac_f32_e32 v15, v105, v177
	v_fmac_f32_e32 v12, v106, v166
	v_fmac_f32_e32 v13, v106, v170
	v_fmac_f32_e32 v14, v106, v174
	v_fmac_f32_e32 v15, v106, v178
	v_fmac_f32_e32 v12, v107, v167
	v_fmac_f32_e32 v13, v107, v171
	v_fmac_f32_e32 v14, v107, v175
	v_fmac_f32_e32 v15, v107, v179
	ds_read_b128 v[164:167], v2 offset:49168
	ds_read_b128 v[168:171], v2 offset:53264
	ds_read_b128 v[172:175], v2 offset:57360
	ds_read_b128 v[176:179], v2 offset:61456
	s_waitcnt lgkmcnt(8)
	v_fmac_f32_e32 v16, v104, v28
	v_fmac_f32_e32 v17, v104, v32
	v_fmac_f32_e32 v20, v104, v36
	v_fmac_f32_e32 v21, v104, v40
	v_fmac_f32_e32 v16, v105, v29
	v_fmac_f32_e32 v17, v105, v33
	v_fmac_f32_e32 v20, v105, v37
	v_fmac_f32_e32 v21, v105, v41
	v_fmac_f32_e32 v16, v106, v30
	v_fmac_f32_e32 v17, v106, v34
	v_fmac_f32_e32 v20, v106, v38
	v_fmac_f32_e32 v21, v106, v42
	v_fmac_f32_e32 v16, v107, v31
	v_fmac_f32_e32 v17, v107, v35
	v_fmac_f32_e32 v20, v107, v39
	v_fmac_f32_e32 v21, v107, v43
	ds_read_b128 v[28:31], v2 offset:32
	ds_read_b128 v[32:35], v2 offset:4128
	ds_read_b128 v[36:39], v2 offset:8224
	ds_read_b128 v[40:43], v2 offset:12320
	s_waitcnt lgkmcnt(8)
	v_fmac_f32_e32 v24, v104, v148
	v_fmac_f32_e32 v25, v104, v152
	v_fmac_f32_e32 v18, v104, v156
	v_fmac_f32_e32 v19, v104, v160
	v_fmac_f32_e32 v24, v105, v149
	v_fmac_f32_e32 v25, v105, v153
	v_fmac_f32_e32 v18, v105, v157
	v_fmac_f32_e32 v19, v105, v161
	v_fmac_f32_e32 v24, v106, v150
	v_fmac_f32_e32 v25, v106, v154
	v_fmac_f32_e32 v18, v106, v158
	v_fmac_f32_e32 v19, v106, v162
	v_fmac_f32_e32 v24, v107, v151
	v_fmac_f32_e32 v25, v107, v155
	v_fmac_f32_e32 v18, v107, v159
	v_fmac_f32_e32 v19, v107, v163
	ds_read_b128 v[148:151], v2 offset:16416
	ds_read_b128 v[152:155], v2 offset:20512
	ds_read_b128 v[156:159], v2 offset:24608
	ds_read_b128 v[160:163], v2 offset:28704
	s_waitcnt lgkmcnt(8)
	v_fmac_f32_e32 v22, v104, v164
	v_fmac_f32_e32 v23, v104, v168
	v_fmac_f32_e32 v26, v104, v172
	v_fmac_f32_e32 v27, v104, v176
	v_fmac_f32_e32 v22, v105, v165
	v_fmac_f32_e32 v23, v105, v169
	v_fmac_f32_e32 v26, v105, v173
	v_fmac_f32_e32 v27, v105, v177
	v_fmac_f32_e32 v22, v106, v166
	v_fmac_f32_e32 v23, v106, v170
	v_fmac_f32_e32 v26, v106, v174
	v_fmac_f32_e32 v27, v106, v178
	v_fmac_f32_e32 v22, v107, v167
	v_fmac_f32_e32 v23, v107, v171
	v_fmac_f32_e32 v26, v107, v175
	v_fmac_f32_e32 v27, v107, v179
	ds_read_b128 v[164:167], v2 offset:32800
	ds_read_b128 v[168:171], v2 offset:36896
	ds_read_b128 v[172:175], v2 offset:40992
	ds_read_b128 v[176:179], v2 offset:45088
	s_waitcnt lgkmcnt(8)
	v_fmac_f32_e32 v12, v108, v28
	v_fmac_f32_e32 v13, v108, v32
	v_fmac_f32_e32 v14, v108, v36
	v_fmac_f32_e32 v15, v108, v40
	v_fmac_f32_e32 v12, v109, v29
	v_fmac_f32_e32 v13, v109, v33
	v_fmac_f32_e32 v14, v109, v37
	v_fmac_f32_e32 v15, v109, v41
	v_fmac_f32_e32 v12, v110, v30
	v_fmac_f32_e32 v13, v110, v34
	v_fmac_f32_e32 v14, v110, v38
	v_fmac_f32_e32 v15, v110, v42
	v_fmac_f32_e32 v12, v111, v31
	v_fmac_f32_e32 v13, v111, v35
	v_fmac_f32_e32 v14, v111, v39
	v_fmac_f32_e32 v15, v111, v43
	ds_read_b128 v[28:31], v2 offset:49184
	ds_read_b128 v[32:35], v2 offset:53280
	ds_read_b128 v[36:39], v2 offset:57376
	ds_read_b128 v[40:43], v2 offset:61472
	s_waitcnt lgkmcnt(8)
	v_fmac_f32_e32 v16, v108, v148
	v_fmac_f32_e32 v17, v108, v152
	v_fmac_f32_e32 v20, v108, v156
	v_fmac_f32_e32 v21, v108, v160
	v_fmac_f32_e32 v16, v109, v149
	v_fmac_f32_e32 v17, v109, v153
	v_fmac_f32_e32 v20, v109, v157
	v_fmac_f32_e32 v21, v109, v161
	v_fmac_f32_e32 v16, v110, v150
	v_fmac_f32_e32 v17, v110, v154
	v_fmac_f32_e32 v20, v110, v158
	v_fmac_f32_e32 v21, v110, v162
	v_fmac_f32_e32 v16, v111, v151
	v_fmac_f32_e32 v17, v111, v155
	v_fmac_f32_e32 v20, v111, v159
	v_fmac_f32_e32 v21, v111, v163
	ds_read_b128 v[148:151], v2 offset:48
	ds_read_b128 v[152:155], v2 offset:4144
	ds_read_b128 v[156:159], v2 offset:8240
	ds_read_b128 v[160:163], v2 offset:12336
	s_waitcnt lgkmcnt(8)
	v_fmac_f32_e32 v24, v108, v164
	v_fmac_f32_e32 v25, v108, v168
	v_fmac_f32_e32 v18, v108, v172
	v_fmac_f32_e32 v19, v108, v176
	v_fmac_f32_e32 v24, v109, v165
	v_fmac_f32_e32 v25, v109, v169
	v_fmac_f32_e32 v18, v109, v173
	v_fmac_f32_e32 v19, v109, v177
	v_fmac_f32_e32 v24, v110, v166
	v_fmac_f32_e32 v25, v110, v170
	v_fmac_f32_e32 v18, v110, v174
	v_fmac_f32_e32 v19, v110, v178
	v_fmac_f32_e32 v24, v111, v167
	v_fmac_f32_e32 v25, v111, v171
	v_fmac_f32_e32 v18, v111, v175
	v_fmac_f32_e32 v19, v111, v179
	ds_read_b128 v[164:167], v2 offset:16432
	ds_read_b128 v[168:171], v2 offset:20528
	ds_read_b128 v[172:175], v2 offset:24624
	ds_read_b128 v[176:179], v2 offset:28720
	s_waitcnt lgkmcnt(8)
	v_fmac_f32_e32 v22, v108, v28
	v_fmac_f32_e32 v23, v108, v32
	v_fmac_f32_e32 v26, v108, v36
	v_fmac_f32_e32 v27, v108, v40
	v_fmac_f32_e32 v22, v109, v29
	v_fmac_f32_e32 v23, v109, v33
	v_fmac_f32_e32 v26, v109, v37
	v_fmac_f32_e32 v27, v109, v41
	v_fmac_f32_e32 v22, v110, v30
	v_fmac_f32_e32 v23, v110, v34
	v_fmac_f32_e32 v26, v110, v38
	v_fmac_f32_e32 v27, v110, v42
	v_fmac_f32_e32 v22, v111, v31
	v_fmac_f32_e32 v23, v111, v35
	v_fmac_f32_e32 v26, v111, v39
	v_fmac_f32_e32 v27, v111, v43
	ds_read_b128 v[28:31], v2 offset:32816
	ds_read_b128 v[32:35], v2 offset:36912
	ds_read_b128 v[36:39], v2 offset:41008
	ds_read_b128 v[40:43], v2 offset:45104
	s_waitcnt lgkmcnt(8)
	v_fmac_f32_e32 v12, v112, v148
	v_fmac_f32_e32 v13, v112, v152
	v_fmac_f32_e32 v14, v112, v156
	v_fmac_f32_e32 v15, v112, v160
	v_fmac_f32_e32 v12, v113, v149
	v_fmac_f32_e32 v13, v113, v153
	v_fmac_f32_e32 v14, v113, v157
	v_fmac_f32_e32 v15, v113, v161
	v_fmac_f32_e32 v12, v114, v150
	v_fmac_f32_e32 v13, v114, v154
	v_fmac_f32_e32 v14, v114, v158
	v_fmac_f32_e32 v15, v114, v162
	v_fmac_f32_e32 v12, v115, v151
	v_fmac_f32_e32 v13, v115, v155
	v_fmac_f32_e32 v14, v115, v159
	v_fmac_f32_e32 v15, v115, v163
	ds_read_b128 v[148:151], v2 offset:49200
	ds_read_b128 v[152:155], v2 offset:53296
	ds_read_b128 v[156:159], v2 offset:57392
	ds_read_b128 v[160:163], v2 offset:61488
	s_waitcnt lgkmcnt(8)
	v_fmac_f32_e32 v16, v112, v164
	v_fmac_f32_e32 v17, v112, v168
	v_fmac_f32_e32 v20, v112, v172
	v_fmac_f32_e32 v21, v112, v176
	v_fmac_f32_e32 v16, v113, v165
	v_fmac_f32_e32 v17, v113, v169
	v_fmac_f32_e32 v20, v113, v173
	v_fmac_f32_e32 v21, v113, v177
	v_fmac_f32_e32 v16, v114, v166
	v_fmac_f32_e32 v17, v114, v170
	v_fmac_f32_e32 v20, v114, v174
	v_fmac_f32_e32 v21, v114, v178
	v_fmac_f32_e32 v16, v115, v167
	v_fmac_f32_e32 v17, v115, v171
	v_fmac_f32_e32 v20, v115, v175
	v_fmac_f32_e32 v21, v115, v179
	ds_read_b128 v[164:167], v2 offset:64
	ds_read_b128 v[168:171], v2 offset:4160
	ds_read_b128 v[172:175], v2 offset:8256
	ds_read_b128 v[176:179], v2 offset:12352
	s_waitcnt lgkmcnt(8)
	v_fmac_f32_e32 v24, v112, v28
	v_fmac_f32_e32 v25, v112, v32
	v_fmac_f32_e32 v18, v112, v36
	v_fmac_f32_e32 v19, v112, v40
	v_fmac_f32_e32 v24, v113, v29
	v_fmac_f32_e32 v25, v113, v33
	v_fmac_f32_e32 v18, v113, v37
	v_fmac_f32_e32 v19, v113, v41
	v_fmac_f32_e32 v24, v114, v30
	v_fmac_f32_e32 v25, v114, v34
	v_fmac_f32_e32 v18, v114, v38
	v_fmac_f32_e32 v19, v114, v42
	v_fmac_f32_e32 v24, v115, v31
	v_fmac_f32_e32 v25, v115, v35
	v_fmac_f32_e32 v18, v115, v39
	v_fmac_f32_e32 v19, v115, v43
	ds_read_b128 v[28:31], v2 offset:16448
	ds_read_b128 v[32:35], v2 offset:20544
	ds_read_b128 v[36:39], v2 offset:24640
	ds_read_b128 v[40:43], v2 offset:28736
	s_waitcnt lgkmcnt(8)
	v_fmac_f32_e32 v22, v112, v148
	v_fmac_f32_e32 v23, v112, v152
	v_fmac_f32_e32 v26, v112, v156
	v_fmac_f32_e32 v27, v112, v160
	v_fmac_f32_e32 v22, v113, v149
	v_fmac_f32_e32 v23, v113, v153
	v_fmac_f32_e32 v26, v113, v157
	v_fmac_f32_e32 v27, v113, v161
	v_fmac_f32_e32 v22, v114, v150
	v_fmac_f32_e32 v23, v114, v154
	v_fmac_f32_e32 v26, v114, v158
	v_fmac_f32_e32 v27, v114, v162
	v_fmac_f32_e32 v22, v115, v151
	v_fmac_f32_e32 v23, v115, v155
	v_fmac_f32_e32 v26, v115, v159
	v_fmac_f32_e32 v27, v115, v163
	global_load_dword v100, v[0:1], off
	v_lshl_add_u64 v[0:1], v[0:1], 0, s[50:51]
	global_load_dword v101, v[0:1], off
	v_lshl_add_u64 v[0:1], v[0:1], 0, s[50:51]
	global_load_dword v102, v[0:1], off
	v_lshl_add_u64 v[0:1], v[0:1], 0, s[50:51]
	global_load_dword v103, v[0:1], off
	v_lshl_add_u64 v[0:1], v[0:1], 0, s[50:51]
	global_load_dword v104, v[0:1], off
	v_lshl_add_u64 v[0:1], v[0:1], 0, s[50:51]
	global_load_dword v105, v[0:1], off
	v_lshl_add_u64 v[0:1], v[0:1], 0, s[50:51]
	global_load_dword v106, v[0:1], off
	v_lshl_add_u64 v[0:1], v[0:1], 0, s[50:51]
	global_load_dword v107, v[0:1], off
	v_lshl_add_u64 v[0:1], v[0:1], 0, s[50:51]
	global_load_dword v108, v[0:1], off
	v_lshl_add_u64 v[0:1], v[0:1], 0, s[50:51]
	global_load_dword v109, v[0:1], off
	v_lshl_add_u64 v[0:1], v[0:1], 0, s[50:51]
	global_load_dword v110, v[0:1], off
	v_lshl_add_u64 v[0:1], v[0:1], 0, s[50:51]
	global_load_dword v111, v[0:1], off
	v_lshl_add_u64 v[0:1], v[0:1], 0, s[50:51]
	global_load_dword v112, v[0:1], off
	v_lshl_add_u64 v[0:1], v[0:1], 0, s[50:51]
	global_load_dword v113, v[0:1], off
	v_lshl_add_u64 v[0:1], v[0:1], 0, s[50:51]
	global_load_dword v114, v[0:1], off
	v_lshl_add_u64 v[0:1], v[0:1], 0, s[50:51]
	global_load_dword v115, v[0:1], off
	v_lshl_add_u64 v[0:1], v[0:1], 0, s[50:51]
	s_waitcnt vmcnt(32)
	ds_read_b128 v[148:151], v2 offset:32832
	ds_read_b128 v[152:155], v2 offset:36928
	ds_read_b128 v[156:159], v2 offset:41024
	ds_read_b128 v[160:163], v2 offset:45120
	s_waitcnt lgkmcnt(8)
	v_fmac_f32_e32 v12, v116, v164
	v_fmac_f32_e32 v13, v116, v168
	v_fmac_f32_e32 v14, v116, v172
	v_fmac_f32_e32 v15, v116, v176
	v_fmac_f32_e32 v12, v117, v165
	v_fmac_f32_e32 v13, v117, v169
	v_fmac_f32_e32 v14, v117, v173
	v_fmac_f32_e32 v15, v117, v177
	v_fmac_f32_e32 v12, v118, v166
	v_fmac_f32_e32 v13, v118, v170
	v_fmac_f32_e32 v14, v118, v174
	v_fmac_f32_e32 v15, v118, v178
	v_fmac_f32_e32 v12, v119, v167
	v_fmac_f32_e32 v13, v119, v171
	v_fmac_f32_e32 v14, v119, v175
	v_fmac_f32_e32 v15, v119, v179
	ds_read_b128 v[164:167], v2 offset:49216
	ds_read_b128 v[168:171], v2 offset:53312
	ds_read_b128 v[172:175], v2 offset:57408
	ds_read_b128 v[176:179], v2 offset:61504
	s_waitcnt lgkmcnt(8)
	v_fmac_f32_e32 v16, v116, v28
	v_fmac_f32_e32 v17, v116, v32
	v_fmac_f32_e32 v20, v116, v36
	v_fmac_f32_e32 v21, v116, v40
	v_fmac_f32_e32 v16, v117, v29
	v_fmac_f32_e32 v17, v117, v33
	v_fmac_f32_e32 v20, v117, v37
	v_fmac_f32_e32 v21, v117, v41
	v_fmac_f32_e32 v16, v118, v30
	v_fmac_f32_e32 v17, v118, v34
	v_fmac_f32_e32 v20, v118, v38
	v_fmac_f32_e32 v21, v118, v42
	v_fmac_f32_e32 v16, v119, v31
	v_fmac_f32_e32 v17, v119, v35
	v_fmac_f32_e32 v20, v119, v39
	v_fmac_f32_e32 v21, v119, v43
	ds_read_b128 v[28:31], v2 offset:80
	ds_read_b128 v[32:35], v2 offset:4176
	ds_read_b128 v[36:39], v2 offset:8272
	ds_read_b128 v[40:43], v2 offset:12368
	s_waitcnt lgkmcnt(8)
	v_fmac_f32_e32 v24, v116, v148
	v_fmac_f32_e32 v25, v116, v152
	v_fmac_f32_e32 v18, v116, v156
	v_fmac_f32_e32 v19, v116, v160
	v_fmac_f32_e32 v24, v117, v149
	v_fmac_f32_e32 v25, v117, v153
	v_fmac_f32_e32 v18, v117, v157
	v_fmac_f32_e32 v19, v117, v161
	v_fmac_f32_e32 v24, v118, v150
	v_fmac_f32_e32 v25, v118, v154
	v_fmac_f32_e32 v18, v118, v158
	v_fmac_f32_e32 v19, v118, v162
	v_fmac_f32_e32 v24, v119, v151
	v_fmac_f32_e32 v25, v119, v155
	v_fmac_f32_e32 v18, v119, v159
	v_fmac_f32_e32 v19, v119, v163
	ds_read_b128 v[148:151], v2 offset:16464
	ds_read_b128 v[152:155], v2 offset:20560
	ds_read_b128 v[156:159], v2 offset:24656
	ds_read_b128 v[160:163], v2 offset:28752
	s_waitcnt lgkmcnt(8)
	v_fmac_f32_e32 v22, v116, v164
	v_fmac_f32_e32 v23, v116, v168
	v_fmac_f32_e32 v26, v116, v172
	v_fmac_f32_e32 v27, v116, v176
	v_fmac_f32_e32 v22, v117, v165
	v_fmac_f32_e32 v23, v117, v169
	v_fmac_f32_e32 v26, v117, v173
	v_fmac_f32_e32 v27, v117, v177
	v_fmac_f32_e32 v22, v118, v166
	v_fmac_f32_e32 v23, v118, v170
	v_fmac_f32_e32 v26, v118, v174
	v_fmac_f32_e32 v27, v118, v178
	v_fmac_f32_e32 v22, v119, v167
	v_fmac_f32_e32 v23, v119, v171
	v_fmac_f32_e32 v26, v119, v175
	v_fmac_f32_e32 v27, v119, v179
	ds_read_b128 v[164:167], v2 offset:32848
	ds_read_b128 v[168:171], v2 offset:36944
	ds_read_b128 v[172:175], v2 offset:41040
	ds_read_b128 v[176:179], v2 offset:45136
	s_waitcnt lgkmcnt(8)
	v_fmac_f32_e32 v12, v120, v28
	v_fmac_f32_e32 v13, v120, v32
	v_fmac_f32_e32 v14, v120, v36
	v_fmac_f32_e32 v15, v120, v40
	v_fmac_f32_e32 v12, v121, v29
	v_fmac_f32_e32 v13, v121, v33
	v_fmac_f32_e32 v14, v121, v37
	v_fmac_f32_e32 v15, v121, v41
	v_fmac_f32_e32 v12, v122, v30
	v_fmac_f32_e32 v13, v122, v34
	v_fmac_f32_e32 v14, v122, v38
	v_fmac_f32_e32 v15, v122, v42
	v_fmac_f32_e32 v12, v123, v31
	v_fmac_f32_e32 v13, v123, v35
	v_fmac_f32_e32 v14, v123, v39
	v_fmac_f32_e32 v15, v123, v43
	ds_read_b128 v[28:31], v2 offset:49232
	ds_read_b128 v[32:35], v2 offset:53328
	ds_read_b128 v[36:39], v2 offset:57424
	ds_read_b128 v[40:43], v2 offset:61520
	s_waitcnt lgkmcnt(8)
	v_fmac_f32_e32 v16, v120, v148
	v_fmac_f32_e32 v17, v120, v152
	v_fmac_f32_e32 v20, v120, v156
	v_fmac_f32_e32 v21, v120, v160
	v_fmac_f32_e32 v16, v121, v149
	v_fmac_f32_e32 v17, v121, v153
	v_fmac_f32_e32 v20, v121, v157
	v_fmac_f32_e32 v21, v121, v161
	v_fmac_f32_e32 v16, v122, v150
	v_fmac_f32_e32 v17, v122, v154
	v_fmac_f32_e32 v20, v122, v158
	v_fmac_f32_e32 v21, v122, v162
	v_fmac_f32_e32 v16, v123, v151
	v_fmac_f32_e32 v17, v123, v155
	v_fmac_f32_e32 v20, v123, v159
	v_fmac_f32_e32 v21, v123, v163
	ds_read_b128 v[148:151], v2 offset:96
	ds_read_b128 v[152:155], v2 offset:4192
	ds_read_b128 v[156:159], v2 offset:8288
	ds_read_b128 v[160:163], v2 offset:12384
	s_waitcnt lgkmcnt(8)
	v_fmac_f32_e32 v24, v120, v164
	v_fmac_f32_e32 v25, v120, v168
	v_fmac_f32_e32 v18, v120, v172
	v_fmac_f32_e32 v19, v120, v176
	v_fmac_f32_e32 v24, v121, v165
	v_fmac_f32_e32 v25, v121, v169
	v_fmac_f32_e32 v18, v121, v173
	v_fmac_f32_e32 v19, v121, v177
	v_fmac_f32_e32 v24, v122, v166
	v_fmac_f32_e32 v25, v122, v170
	v_fmac_f32_e32 v18, v122, v174
	v_fmac_f32_e32 v19, v122, v178
	v_fmac_f32_e32 v24, v123, v167
	v_fmac_f32_e32 v25, v123, v171
	v_fmac_f32_e32 v18, v123, v175
	v_fmac_f32_e32 v19, v123, v179
	ds_read_b128 v[164:167], v2 offset:16480
	ds_read_b128 v[168:171], v2 offset:20576
	ds_read_b128 v[172:175], v2 offset:24672
	ds_read_b128 v[176:179], v2 offset:28768
	s_waitcnt lgkmcnt(8)
	v_fmac_f32_e32 v22, v120, v28
	v_fmac_f32_e32 v23, v120, v32
	v_fmac_f32_e32 v26, v120, v36
	v_fmac_f32_e32 v27, v120, v40
	v_fmac_f32_e32 v22, v121, v29
	v_fmac_f32_e32 v23, v121, v33
	v_fmac_f32_e32 v26, v121, v37
	v_fmac_f32_e32 v27, v121, v41
	v_fmac_f32_e32 v22, v122, v30
	v_fmac_f32_e32 v23, v122, v34
	v_fmac_f32_e32 v26, v122, v38
	v_fmac_f32_e32 v27, v122, v42
	v_fmac_f32_e32 v22, v123, v31
	v_fmac_f32_e32 v23, v123, v35
	v_fmac_f32_e32 v26, v123, v39
	v_fmac_f32_e32 v27, v123, v43
	ds_read_b128 v[28:31], v2 offset:32864
	ds_read_b128 v[32:35], v2 offset:36960
	ds_read_b128 v[36:39], v2 offset:41056
	ds_read_b128 v[40:43], v2 offset:45152
	s_waitcnt lgkmcnt(8)
	v_fmac_f32_e32 v12, v124, v148
	v_fmac_f32_e32 v13, v124, v152
	v_fmac_f32_e32 v14, v124, v156
	v_fmac_f32_e32 v15, v124, v160
	v_fmac_f32_e32 v12, v125, v149
	v_fmac_f32_e32 v13, v125, v153
	v_fmac_f32_e32 v14, v125, v157
	v_fmac_f32_e32 v15, v125, v161
	v_fmac_f32_e32 v12, v126, v150
	v_fmac_f32_e32 v13, v126, v154
	v_fmac_f32_e32 v14, v126, v158
	v_fmac_f32_e32 v15, v126, v162
	v_fmac_f32_e32 v12, v127, v151
	v_fmac_f32_e32 v13, v127, v155
	v_fmac_f32_e32 v14, v127, v159
	v_fmac_f32_e32 v15, v127, v163
	ds_read_b128 v[148:151], v2 offset:49248
	ds_read_b128 v[152:155], v2 offset:53344
	ds_read_b128 v[156:159], v2 offset:57440
	ds_read_b128 v[160:163], v2 offset:61536
	s_waitcnt lgkmcnt(8)
	v_fmac_f32_e32 v16, v124, v164
	v_fmac_f32_e32 v17, v124, v168
	v_fmac_f32_e32 v20, v124, v172
	v_fmac_f32_e32 v21, v124, v176
	v_fmac_f32_e32 v16, v125, v165
	v_fmac_f32_e32 v17, v125, v169
	v_fmac_f32_e32 v20, v125, v173
	v_fmac_f32_e32 v21, v125, v177
	v_fmac_f32_e32 v16, v126, v166
	v_fmac_f32_e32 v17, v126, v170
	v_fmac_f32_e32 v20, v126, v174
	v_fmac_f32_e32 v21, v126, v178
	v_fmac_f32_e32 v16, v127, v167
	v_fmac_f32_e32 v17, v127, v171
	v_fmac_f32_e32 v20, v127, v175
	v_fmac_f32_e32 v21, v127, v179
	ds_read_b128 v[164:167], v2 offset:112
	ds_read_b128 v[168:171], v2 offset:4208
	ds_read_b128 v[172:175], v2 offset:8304
	ds_read_b128 v[176:179], v2 offset:12400
	s_waitcnt lgkmcnt(8)
	v_fmac_f32_e32 v24, v124, v28
	v_fmac_f32_e32 v25, v124, v32
	v_fmac_f32_e32 v18, v124, v36
	v_fmac_f32_e32 v19, v124, v40
	v_fmac_f32_e32 v24, v125, v29
	v_fmac_f32_e32 v25, v125, v33
	v_fmac_f32_e32 v18, v125, v37
	v_fmac_f32_e32 v19, v125, v41
	v_fmac_f32_e32 v24, v126, v30
	v_fmac_f32_e32 v25, v126, v34
	v_fmac_f32_e32 v18, v126, v38
	v_fmac_f32_e32 v19, v126, v42
	v_fmac_f32_e32 v24, v127, v31
	v_fmac_f32_e32 v25, v127, v35
	v_fmac_f32_e32 v18, v127, v39
	v_fmac_f32_e32 v19, v127, v43
	ds_read_b128 v[28:31], v2 offset:16496
	ds_read_b128 v[32:35], v2 offset:20592
	ds_read_b128 v[36:39], v2 offset:24688
	ds_read_b128 v[40:43], v2 offset:28784
	s_waitcnt lgkmcnt(8)
	v_fmac_f32_e32 v22, v124, v148
	v_fmac_f32_e32 v23, v124, v152
	v_fmac_f32_e32 v26, v124, v156
	v_fmac_f32_e32 v27, v124, v160
	v_fmac_f32_e32 v22, v125, v149
	v_fmac_f32_e32 v23, v125, v153
	v_fmac_f32_e32 v26, v125, v157
	v_fmac_f32_e32 v27, v125, v161
	v_fmac_f32_e32 v22, v126, v150
	v_fmac_f32_e32 v23, v126, v154
	v_fmac_f32_e32 v26, v126, v158
	v_fmac_f32_e32 v27, v126, v162
	v_fmac_f32_e32 v22, v127, v151
	v_fmac_f32_e32 v23, v127, v155
	v_fmac_f32_e32 v26, v127, v159
	v_fmac_f32_e32 v27, v127, v163
	ds_read_b128 v[148:151], v2 offset:32880
	ds_read_b128 v[152:155], v2 offset:36976
	ds_read_b128 v[156:159], v2 offset:41072
	ds_read_b128 v[160:163], v2 offset:45168
	s_waitcnt lgkmcnt(8)
	v_fmac_f32_e32 v12, v128, v164
	v_fmac_f32_e32 v13, v128, v168
	v_fmac_f32_e32 v14, v128, v172
	v_fmac_f32_e32 v15, v128, v176
	v_fmac_f32_e32 v12, v129, v165
	v_fmac_f32_e32 v13, v129, v169
	v_fmac_f32_e32 v14, v129, v173
	v_fmac_f32_e32 v15, v129, v177
	v_fmac_f32_e32 v12, v130, v166
	v_fmac_f32_e32 v13, v130, v170
	v_fmac_f32_e32 v14, v130, v174
	v_fmac_f32_e32 v15, v130, v178
	v_fmac_f32_e32 v12, v131, v167
	v_fmac_f32_e32 v13, v131, v171
	v_fmac_f32_e32 v14, v131, v175
	v_fmac_f32_e32 v15, v131, v179
	ds_read_b128 v[164:167], v2 offset:49264
	ds_read_b128 v[168:171], v2 offset:53360
	ds_read_b128 v[172:175], v2 offset:57456
	ds_read_b128 v[176:179], v2 offset:61552
	s_waitcnt lgkmcnt(8)
	v_fmac_f32_e32 v16, v128, v28
	v_fmac_f32_e32 v17, v128, v32
	v_fmac_f32_e32 v20, v128, v36
	v_fmac_f32_e32 v21, v128, v40
	v_fmac_f32_e32 v16, v129, v29
	v_fmac_f32_e32 v17, v129, v33
	v_fmac_f32_e32 v20, v129, v37
	v_fmac_f32_e32 v21, v129, v41
	v_fmac_f32_e32 v16, v130, v30
	v_fmac_f32_e32 v17, v130, v34
	v_fmac_f32_e32 v20, v130, v38
	v_fmac_f32_e32 v21, v130, v42
	v_fmac_f32_e32 v16, v131, v31
	v_fmac_f32_e32 v17, v131, v35
	v_fmac_f32_e32 v20, v131, v39
	v_fmac_f32_e32 v21, v131, v43
	ds_read_b128 v[28:31], v2 offset:128
	ds_read_b128 v[32:35], v2 offset:4224
	ds_read_b128 v[36:39], v2 offset:8320
	ds_read_b128 v[40:43], v2 offset:12416
	s_waitcnt lgkmcnt(8)
	v_fmac_f32_e32 v24, v128, v148
	v_fmac_f32_e32 v25, v128, v152
	v_fmac_f32_e32 v18, v128, v156
	v_fmac_f32_e32 v19, v128, v160
	v_fmac_f32_e32 v24, v129, v149
	v_fmac_f32_e32 v25, v129, v153
	v_fmac_f32_e32 v18, v129, v157
	v_fmac_f32_e32 v19, v129, v161
	v_fmac_f32_e32 v24, v130, v150
	v_fmac_f32_e32 v25, v130, v154
	v_fmac_f32_e32 v18, v130, v158
	v_fmac_f32_e32 v19, v130, v162
	v_fmac_f32_e32 v24, v131, v151
	v_fmac_f32_e32 v25, v131, v155
	v_fmac_f32_e32 v18, v131, v159
	v_fmac_f32_e32 v19, v131, v163
	ds_read_b128 v[148:151], v2 offset:16512
	ds_read_b128 v[152:155], v2 offset:20608
	ds_read_b128 v[156:159], v2 offset:24704
	ds_read_b128 v[160:163], v2 offset:28800
	s_waitcnt lgkmcnt(8)
	v_fmac_f32_e32 v22, v128, v164
	v_fmac_f32_e32 v23, v128, v168
	v_fmac_f32_e32 v26, v128, v172
	v_fmac_f32_e32 v27, v128, v176
	v_fmac_f32_e32 v22, v129, v165
	v_fmac_f32_e32 v23, v129, v169
	v_fmac_f32_e32 v26, v129, v173
	v_fmac_f32_e32 v27, v129, v177
	v_fmac_f32_e32 v22, v130, v166
	v_fmac_f32_e32 v23, v130, v170
	v_fmac_f32_e32 v26, v130, v174
	v_fmac_f32_e32 v27, v130, v178
	v_fmac_f32_e32 v22, v131, v167
	v_fmac_f32_e32 v23, v131, v171
	v_fmac_f32_e32 v26, v131, v175
	v_fmac_f32_e32 v27, v131, v179
	global_load_dword v116, v[0:1], off
	v_lshl_add_u64 v[0:1], v[0:1], 0, s[50:51]
	global_load_dword v117, v[0:1], off
	v_lshl_add_u64 v[0:1], v[0:1], 0, s[50:51]
	global_load_dword v118, v[0:1], off
	v_lshl_add_u64 v[0:1], v[0:1], 0, s[50:51]
	global_load_dword v119, v[0:1], off
	v_lshl_add_u64 v[0:1], v[0:1], 0, s[50:51]
	global_load_dword v120, v[0:1], off
	v_lshl_add_u64 v[0:1], v[0:1], 0, s[50:51]
	global_load_dword v121, v[0:1], off
	v_lshl_add_u64 v[0:1], v[0:1], 0, s[50:51]
	global_load_dword v122, v[0:1], off
	v_lshl_add_u64 v[0:1], v[0:1], 0, s[50:51]
	global_load_dword v123, v[0:1], off
	v_lshl_add_u64 v[0:1], v[0:1], 0, s[50:51]
	global_load_dword v124, v[0:1], off
	v_lshl_add_u64 v[0:1], v[0:1], 0, s[50:51]
	global_load_dword v125, v[0:1], off
	v_lshl_add_u64 v[0:1], v[0:1], 0, s[50:51]
	global_load_dword v126, v[0:1], off
	v_lshl_add_u64 v[0:1], v[0:1], 0, s[50:51]
	global_load_dword v127, v[0:1], off
	v_lshl_add_u64 v[0:1], v[0:1], 0, s[50:51]
	global_load_dword v128, v[0:1], off
	v_lshl_add_u64 v[0:1], v[0:1], 0, s[50:51]
	global_load_dword v129, v[0:1], off
	v_lshl_add_u64 v[0:1], v[0:1], 0, s[50:51]
	global_load_dword v130, v[0:1], off
	v_lshl_add_u64 v[0:1], v[0:1], 0, s[50:51]
	global_load_dword v131, v[0:1], off
	v_lshl_add_u64 v[0:1], v[0:1], 0, s[50:51]
	s_waitcnt vmcnt(32)
	ds_read_b128 v[164:167], v2 offset:32896
	ds_read_b128 v[168:171], v2 offset:36992
	ds_read_b128 v[172:175], v2 offset:41088
	ds_read_b128 v[176:179], v2 offset:45184
	s_waitcnt lgkmcnt(8)
	v_fmac_f32_e32 v12, v132, v28
	v_fmac_f32_e32 v13, v132, v32
	v_fmac_f32_e32 v14, v132, v36
	v_fmac_f32_e32 v15, v132, v40
	v_fmac_f32_e32 v12, v133, v29
	v_fmac_f32_e32 v13, v133, v33
	v_fmac_f32_e32 v14, v133, v37
	v_fmac_f32_e32 v15, v133, v41
	v_fmac_f32_e32 v12, v134, v30
	v_fmac_f32_e32 v13, v134, v34
	v_fmac_f32_e32 v14, v134, v38
	v_fmac_f32_e32 v15, v134, v42
	v_fmac_f32_e32 v12, v135, v31
	v_fmac_f32_e32 v13, v135, v35
	v_fmac_f32_e32 v14, v135, v39
	v_fmac_f32_e32 v15, v135, v43
	ds_read_b128 v[28:31], v2 offset:49280
	ds_read_b128 v[32:35], v2 offset:53376
	ds_read_b128 v[36:39], v2 offset:57472
	ds_read_b128 v[40:43], v2 offset:61568
	s_waitcnt lgkmcnt(8)
	v_fmac_f32_e32 v16, v132, v148
	v_fmac_f32_e32 v17, v132, v152
	v_fmac_f32_e32 v20, v132, v156
	v_fmac_f32_e32 v21, v132, v160
	v_fmac_f32_e32 v16, v133, v149
	v_fmac_f32_e32 v17, v133, v153
	v_fmac_f32_e32 v20, v133, v157
	v_fmac_f32_e32 v21, v133, v161
	v_fmac_f32_e32 v16, v134, v150
	v_fmac_f32_e32 v17, v134, v154
	v_fmac_f32_e32 v20, v134, v158
	v_fmac_f32_e32 v21, v134, v162
	v_fmac_f32_e32 v16, v135, v151
	v_fmac_f32_e32 v17, v135, v155
	v_fmac_f32_e32 v20, v135, v159
	v_fmac_f32_e32 v21, v135, v163
	ds_read_b128 v[148:151], v2 offset:144
	ds_read_b128 v[152:155], v2 offset:4240
	ds_read_b128 v[156:159], v2 offset:8336
	ds_read_b128 v[160:163], v2 offset:12432
	s_waitcnt lgkmcnt(8)
	v_fmac_f32_e32 v24, v132, v164
	v_fmac_f32_e32 v25, v132, v168
	v_fmac_f32_e32 v18, v132, v172
	v_fmac_f32_e32 v19, v132, v176
	v_fmac_f32_e32 v24, v133, v165
	v_fmac_f32_e32 v25, v133, v169
	v_fmac_f32_e32 v18, v133, v173
	v_fmac_f32_e32 v19, v133, v177
	v_fmac_f32_e32 v24, v134, v166
	v_fmac_f32_e32 v25, v134, v170
	v_fmac_f32_e32 v18, v134, v174
	v_fmac_f32_e32 v19, v134, v178
	v_fmac_f32_e32 v24, v135, v167
	v_fmac_f32_e32 v25, v135, v171
	v_fmac_f32_e32 v18, v135, v175
	v_fmac_f32_e32 v19, v135, v179
	ds_read_b128 v[164:167], v2 offset:16528
	ds_read_b128 v[168:171], v2 offset:20624
	ds_read_b128 v[172:175], v2 offset:24720
	ds_read_b128 v[176:179], v2 offset:28816
	s_waitcnt lgkmcnt(8)
	v_fmac_f32_e32 v22, v132, v28
	v_fmac_f32_e32 v23, v132, v32
	v_fmac_f32_e32 v26, v132, v36
	v_fmac_f32_e32 v27, v132, v40
	v_fmac_f32_e32 v22, v133, v29
	v_fmac_f32_e32 v23, v133, v33
	v_fmac_f32_e32 v26, v133, v37
	v_fmac_f32_e32 v27, v133, v41
	v_fmac_f32_e32 v22, v134, v30
	v_fmac_f32_e32 v23, v134, v34
	v_fmac_f32_e32 v26, v134, v38
	v_fmac_f32_e32 v27, v134, v42
	v_fmac_f32_e32 v22, v135, v31
	v_fmac_f32_e32 v23, v135, v35
	v_fmac_f32_e32 v26, v135, v39
	v_fmac_f32_e32 v27, v135, v43
	ds_read_b128 v[28:31], v2 offset:32912
	ds_read_b128 v[32:35], v2 offset:37008
	ds_read_b128 v[36:39], v2 offset:41104
	ds_read_b128 v[40:43], v2 offset:45200
	s_waitcnt lgkmcnt(8)
	v_fmac_f32_e32 v12, v136, v148
	v_fmac_f32_e32 v13, v136, v152
	v_fmac_f32_e32 v14, v136, v156
	v_fmac_f32_e32 v15, v136, v160
	v_fmac_f32_e32 v12, v137, v149
	v_fmac_f32_e32 v13, v137, v153
	v_fmac_f32_e32 v14, v137, v157
	v_fmac_f32_e32 v15, v137, v161
	v_fmac_f32_e32 v12, v138, v150
	v_fmac_f32_e32 v13, v138, v154
	v_fmac_f32_e32 v14, v138, v158
	v_fmac_f32_e32 v15, v138, v162
	v_fmac_f32_e32 v12, v139, v151
	v_fmac_f32_e32 v13, v139, v155
	v_fmac_f32_e32 v14, v139, v159
	v_fmac_f32_e32 v15, v139, v163
	ds_read_b128 v[148:151], v2 offset:49296
	ds_read_b128 v[152:155], v2 offset:53392
	ds_read_b128 v[156:159], v2 offset:57488
	ds_read_b128 v[160:163], v2 offset:61584
	s_waitcnt lgkmcnt(8)
	v_fmac_f32_e32 v16, v136, v164
	v_fmac_f32_e32 v17, v136, v168
	v_fmac_f32_e32 v20, v136, v172
	v_fmac_f32_e32 v21, v136, v176
	v_fmac_f32_e32 v16, v137, v165
	v_fmac_f32_e32 v17, v137, v169
	v_fmac_f32_e32 v20, v137, v173
	v_fmac_f32_e32 v21, v137, v177
	v_fmac_f32_e32 v16, v138, v166
	v_fmac_f32_e32 v17, v138, v170
	v_fmac_f32_e32 v20, v138, v174
	v_fmac_f32_e32 v21, v138, v178
	v_fmac_f32_e32 v16, v139, v167
	v_fmac_f32_e32 v17, v139, v171
	v_fmac_f32_e32 v20, v139, v175
	v_fmac_f32_e32 v21, v139, v179
	ds_read_b128 v[164:167], v2 offset:160
	ds_read_b128 v[168:171], v2 offset:4256
	ds_read_b128 v[172:175], v2 offset:8352
	ds_read_b128 v[176:179], v2 offset:12448
	s_waitcnt lgkmcnt(8)
	v_fmac_f32_e32 v24, v136, v28
	v_fmac_f32_e32 v25, v136, v32
	v_fmac_f32_e32 v18, v136, v36
	v_fmac_f32_e32 v19, v136, v40
	v_fmac_f32_e32 v24, v137, v29
	v_fmac_f32_e32 v25, v137, v33
	v_fmac_f32_e32 v18, v137, v37
	v_fmac_f32_e32 v19, v137, v41
	v_fmac_f32_e32 v24, v138, v30
	v_fmac_f32_e32 v25, v138, v34
	v_fmac_f32_e32 v18, v138, v38
	v_fmac_f32_e32 v19, v138, v42
	v_fmac_f32_e32 v24, v139, v31
	v_fmac_f32_e32 v25, v139, v35
	v_fmac_f32_e32 v18, v139, v39
	v_fmac_f32_e32 v19, v139, v43
	ds_read_b128 v[28:31], v2 offset:16544
	ds_read_b128 v[32:35], v2 offset:20640
	ds_read_b128 v[36:39], v2 offset:24736
	ds_read_b128 v[40:43], v2 offset:28832
	s_waitcnt lgkmcnt(8)
	v_fmac_f32_e32 v22, v136, v148
	v_fmac_f32_e32 v23, v136, v152
	v_fmac_f32_e32 v26, v136, v156
	v_fmac_f32_e32 v27, v136, v160
	v_fmac_f32_e32 v22, v137, v149
	v_fmac_f32_e32 v23, v137, v153
	v_fmac_f32_e32 v26, v137, v157
	v_fmac_f32_e32 v27, v137, v161
	v_fmac_f32_e32 v22, v138, v150
	v_fmac_f32_e32 v23, v138, v154
	v_fmac_f32_e32 v26, v138, v158
	v_fmac_f32_e32 v27, v138, v162
	v_fmac_f32_e32 v22, v139, v151
	v_fmac_f32_e32 v23, v139, v155
	v_fmac_f32_e32 v26, v139, v159
	v_fmac_f32_e32 v27, v139, v163
	ds_read_b128 v[148:151], v2 offset:32928
	ds_read_b128 v[152:155], v2 offset:37024
	ds_read_b128 v[156:159], v2 offset:41120
	ds_read_b128 v[160:163], v2 offset:45216
	s_waitcnt lgkmcnt(8)
	v_fmac_f32_e32 v12, v140, v164
	v_fmac_f32_e32 v13, v140, v168
	v_fmac_f32_e32 v14, v140, v172
	v_fmac_f32_e32 v15, v140, v176
	v_fmac_f32_e32 v12, v141, v165
	v_fmac_f32_e32 v13, v141, v169
	v_fmac_f32_e32 v14, v141, v173
	v_fmac_f32_e32 v15, v141, v177
	v_fmac_f32_e32 v12, v142, v166
	v_fmac_f32_e32 v13, v142, v170
	v_fmac_f32_e32 v14, v142, v174
	v_fmac_f32_e32 v15, v142, v178
	v_fmac_f32_e32 v12, v143, v167
	v_fmac_f32_e32 v13, v143, v171
	v_fmac_f32_e32 v14, v143, v175
	v_fmac_f32_e32 v15, v143, v179
	ds_read_b128 v[164:167], v2 offset:49312
	ds_read_b128 v[168:171], v2 offset:53408
	ds_read_b128 v[172:175], v2 offset:57504
	ds_read_b128 v[176:179], v2 offset:61600
	s_waitcnt lgkmcnt(8)
	v_fmac_f32_e32 v16, v140, v28
	v_fmac_f32_e32 v17, v140, v32
	v_fmac_f32_e32 v20, v140, v36
	v_fmac_f32_e32 v21, v140, v40
	v_fmac_f32_e32 v16, v141, v29
	v_fmac_f32_e32 v17, v141, v33
	v_fmac_f32_e32 v20, v141, v37
	v_fmac_f32_e32 v21, v141, v41
	v_fmac_f32_e32 v16, v142, v30
	v_fmac_f32_e32 v17, v142, v34
	v_fmac_f32_e32 v20, v142, v38
	v_fmac_f32_e32 v21, v142, v42
	v_fmac_f32_e32 v16, v143, v31
	v_fmac_f32_e32 v17, v143, v35
	v_fmac_f32_e32 v20, v143, v39
	v_fmac_f32_e32 v21, v143, v43
	ds_read_b128 v[28:31], v2 offset:176
	ds_read_b128 v[32:35], v2 offset:4272
	ds_read_b128 v[36:39], v2 offset:8368
	ds_read_b128 v[40:43], v2 offset:12464
	s_waitcnt lgkmcnt(8)
	v_fmac_f32_e32 v24, v140, v148
	v_fmac_f32_e32 v25, v140, v152
	v_fmac_f32_e32 v18, v140, v156
	v_fmac_f32_e32 v19, v140, v160
	v_fmac_f32_e32 v24, v141, v149
	v_fmac_f32_e32 v25, v141, v153
	v_fmac_f32_e32 v18, v141, v157
	v_fmac_f32_e32 v19, v141, v161
	v_fmac_f32_e32 v24, v142, v150
	v_fmac_f32_e32 v25, v142, v154
	v_fmac_f32_e32 v18, v142, v158
	v_fmac_f32_e32 v19, v142, v162
	v_fmac_f32_e32 v24, v143, v151
	v_fmac_f32_e32 v25, v143, v155
	v_fmac_f32_e32 v18, v143, v159
	v_fmac_f32_e32 v19, v143, v163
	ds_read_b128 v[148:151], v2 offset:16560
	ds_read_b128 v[152:155], v2 offset:20656
	ds_read_b128 v[156:159], v2 offset:24752
	ds_read_b128 v[160:163], v2 offset:28848
	s_waitcnt lgkmcnt(8)
	v_fmac_f32_e32 v22, v140, v164
	v_fmac_f32_e32 v23, v140, v168
	v_fmac_f32_e32 v26, v140, v172
	v_fmac_f32_e32 v27, v140, v176
	v_fmac_f32_e32 v22, v141, v165
	v_fmac_f32_e32 v23, v141, v169
	v_fmac_f32_e32 v26, v141, v173
	v_fmac_f32_e32 v27, v141, v177
	v_fmac_f32_e32 v22, v142, v166
	v_fmac_f32_e32 v23, v142, v170
	v_fmac_f32_e32 v26, v142, v174
	v_fmac_f32_e32 v27, v142, v178
	v_fmac_f32_e32 v22, v143, v167
	v_fmac_f32_e32 v23, v143, v171
	v_fmac_f32_e32 v26, v143, v175
	v_fmac_f32_e32 v27, v143, v179
	ds_read_b128 v[164:167], v2 offset:32944
	ds_read_b128 v[168:171], v2 offset:37040
	ds_read_b128 v[172:175], v2 offset:41136
	ds_read_b128 v[176:179], v2 offset:45232
	s_waitcnt lgkmcnt(8)
	v_fmac_f32_e32 v12, v144, v28
	v_fmac_f32_e32 v13, v144, v32
	v_fmac_f32_e32 v14, v144, v36
	v_fmac_f32_e32 v15, v144, v40
	v_fmac_f32_e32 v12, v145, v29
	v_fmac_f32_e32 v13, v145, v33
	v_fmac_f32_e32 v14, v145, v37
	v_fmac_f32_e32 v15, v145, v41
	v_fmac_f32_e32 v12, v146, v30
	v_fmac_f32_e32 v13, v146, v34
	v_fmac_f32_e32 v14, v146, v38
	v_fmac_f32_e32 v15, v146, v42
	v_fmac_f32_e32 v12, v147, v31
	v_fmac_f32_e32 v13, v147, v35
	v_fmac_f32_e32 v14, v147, v39
	v_fmac_f32_e32 v15, v147, v43
	ds_read_b128 v[28:31], v2 offset:49328
	ds_read_b128 v[32:35], v2 offset:53424
	ds_read_b128 v[36:39], v2 offset:57520
	ds_read_b128 v[40:43], v2 offset:61616
	s_waitcnt lgkmcnt(8)
	v_fmac_f32_e32 v16, v144, v148
	v_fmac_f32_e32 v17, v144, v152
	v_fmac_f32_e32 v20, v144, v156
	v_fmac_f32_e32 v21, v144, v160
	v_fmac_f32_e32 v16, v145, v149
	v_fmac_f32_e32 v17, v145, v153
	v_fmac_f32_e32 v20, v145, v157
	v_fmac_f32_e32 v21, v145, v161
	v_fmac_f32_e32 v16, v146, v150
	v_fmac_f32_e32 v17, v146, v154
	v_fmac_f32_e32 v20, v146, v158
	v_fmac_f32_e32 v21, v146, v162
	v_fmac_f32_e32 v16, v147, v151
	v_fmac_f32_e32 v17, v147, v155
	v_fmac_f32_e32 v20, v147, v159
	v_fmac_f32_e32 v21, v147, v163
	ds_read_b128 v[148:151], v2 offset:192
	ds_read_b128 v[152:155], v2 offset:4288
	ds_read_b128 v[156:159], v2 offset:8384
	ds_read_b128 v[160:163], v2 offset:12480
	s_waitcnt lgkmcnt(8)
	v_fmac_f32_e32 v24, v144, v164
	v_fmac_f32_e32 v25, v144, v168
	v_fmac_f32_e32 v18, v144, v172
	v_fmac_f32_e32 v19, v144, v176
	v_fmac_f32_e32 v24, v145, v165
	v_fmac_f32_e32 v25, v145, v169
	v_fmac_f32_e32 v18, v145, v173
	v_fmac_f32_e32 v19, v145, v177
	v_fmac_f32_e32 v24, v146, v166
	v_fmac_f32_e32 v25, v146, v170
	v_fmac_f32_e32 v18, v146, v174
	v_fmac_f32_e32 v19, v146, v178
	v_fmac_f32_e32 v24, v147, v167
	v_fmac_f32_e32 v25, v147, v171
	v_fmac_f32_e32 v18, v147, v175
	v_fmac_f32_e32 v19, v147, v179
	ds_read_b128 v[164:167], v2 offset:16576
	ds_read_b128 v[168:171], v2 offset:20672
	ds_read_b128 v[172:175], v2 offset:24768
	ds_read_b128 v[176:179], v2 offset:28864
	s_waitcnt lgkmcnt(8)
	v_fmac_f32_e32 v22, v144, v28
	v_fmac_f32_e32 v23, v144, v32
	v_fmac_f32_e32 v26, v144, v36
	v_fmac_f32_e32 v27, v144, v40
	v_fmac_f32_e32 v22, v145, v29
	v_fmac_f32_e32 v23, v145, v33
	v_fmac_f32_e32 v26, v145, v37
	v_fmac_f32_e32 v27, v145, v41
	v_fmac_f32_e32 v22, v146, v30
	v_fmac_f32_e32 v23, v146, v34
	v_fmac_f32_e32 v26, v146, v38
	v_fmac_f32_e32 v27, v146, v42
	v_fmac_f32_e32 v22, v147, v31
	v_fmac_f32_e32 v23, v147, v35
	v_fmac_f32_e32 v26, v147, v39
	v_fmac_f32_e32 v27, v147, v43
	global_load_dword v132, v[0:1], off
	v_lshl_add_u64 v[0:1], v[0:1], 0, s[50:51]
	global_load_dword v133, v[0:1], off
	v_lshl_add_u64 v[0:1], v[0:1], 0, s[50:51]
	global_load_dword v134, v[0:1], off
	v_lshl_add_u64 v[0:1], v[0:1], 0, s[50:51]
	global_load_dword v135, v[0:1], off
	v_lshl_add_u64 v[0:1], v[0:1], 0, s[50:51]
	global_load_dword v136, v[0:1], off
	v_lshl_add_u64 v[0:1], v[0:1], 0, s[50:51]
	global_load_dword v137, v[0:1], off
	v_lshl_add_u64 v[0:1], v[0:1], 0, s[50:51]
	global_load_dword v138, v[0:1], off
	v_lshl_add_u64 v[0:1], v[0:1], 0, s[50:51]
	global_load_dword v139, v[0:1], off
	v_lshl_add_u64 v[0:1], v[0:1], 0, s[50:51]
	global_load_dword v140, v[0:1], off
	v_lshl_add_u64 v[0:1], v[0:1], 0, s[50:51]
	global_load_dword v141, v[0:1], off
	v_lshl_add_u64 v[0:1], v[0:1], 0, s[50:51]
	global_load_dword v142, v[0:1], off
	v_lshl_add_u64 v[0:1], v[0:1], 0, s[50:51]
	global_load_dword v143, v[0:1], off
	v_lshl_add_u64 v[0:1], v[0:1], 0, s[50:51]
	global_load_dword v144, v[0:1], off
	v_lshl_add_u64 v[0:1], v[0:1], 0, s[50:51]
	global_load_dword v145, v[0:1], off
	v_lshl_add_u64 v[0:1], v[0:1], 0, s[50:51]
	global_load_dword v146, v[0:1], off
	v_lshl_add_u64 v[0:1], v[0:1], 0, s[50:51]
	global_load_dword v147, v[0:1], off
	v_lshl_add_u64 v[0:1], v[0:1], 0, s[50:51]
	s_waitcnt vmcnt(32)
	ds_read_b128 v[28:31], v2 offset:32960
	ds_read_b128 v[32:35], v2 offset:37056
	ds_read_b128 v[36:39], v2 offset:41152
	ds_read_b128 v[40:43], v2 offset:45248
	s_waitcnt lgkmcnt(8)
	v_fmac_f32_e32 v12, v100, v148
	v_fmac_f32_e32 v13, v100, v152
	v_fmac_f32_e32 v14, v100, v156
	v_fmac_f32_e32 v15, v100, v160
	v_fmac_f32_e32 v12, v101, v149
	v_fmac_f32_e32 v13, v101, v153
	v_fmac_f32_e32 v14, v101, v157
	v_fmac_f32_e32 v15, v101, v161
	v_fmac_f32_e32 v12, v102, v150
	v_fmac_f32_e32 v13, v102, v154
	v_fmac_f32_e32 v14, v102, v158
	v_fmac_f32_e32 v15, v102, v162
	v_fmac_f32_e32 v12, v103, v151
	v_fmac_f32_e32 v13, v103, v155
	v_fmac_f32_e32 v14, v103, v159
	v_fmac_f32_e32 v15, v103, v163
	ds_read_b128 v[148:151], v2 offset:49344
	ds_read_b128 v[152:155], v2 offset:53440
	ds_read_b128 v[156:159], v2 offset:57536
	ds_read_b128 v[160:163], v2 offset:61632
	s_waitcnt lgkmcnt(8)
	v_fmac_f32_e32 v16, v100, v164
	v_fmac_f32_e32 v17, v100, v168
	v_fmac_f32_e32 v20, v100, v172
	v_fmac_f32_e32 v21, v100, v176
	v_fmac_f32_e32 v16, v101, v165
	v_fmac_f32_e32 v17, v101, v169
	v_fmac_f32_e32 v20, v101, v173
	v_fmac_f32_e32 v21, v101, v177
	v_fmac_f32_e32 v16, v102, v166
	v_fmac_f32_e32 v17, v102, v170
	v_fmac_f32_e32 v20, v102, v174
	v_fmac_f32_e32 v21, v102, v178
	v_fmac_f32_e32 v16, v103, v167
	v_fmac_f32_e32 v17, v103, v171
	v_fmac_f32_e32 v20, v103, v175
	v_fmac_f32_e32 v21, v103, v179
	ds_read_b128 v[164:167], v2 offset:208
	ds_read_b128 v[168:171], v2 offset:4304
	ds_read_b128 v[172:175], v2 offset:8400
	ds_read_b128 v[176:179], v2 offset:12496
	s_waitcnt lgkmcnt(8)
	v_fmac_f32_e32 v24, v100, v28
	v_fmac_f32_e32 v25, v100, v32
	v_fmac_f32_e32 v18, v100, v36
	v_fmac_f32_e32 v19, v100, v40
	v_fmac_f32_e32 v24, v101, v29
	v_fmac_f32_e32 v25, v101, v33
	v_fmac_f32_e32 v18, v101, v37
	v_fmac_f32_e32 v19, v101, v41
	v_fmac_f32_e32 v24, v102, v30
	v_fmac_f32_e32 v25, v102, v34
	v_fmac_f32_e32 v18, v102, v38
	v_fmac_f32_e32 v19, v102, v42
	v_fmac_f32_e32 v24, v103, v31
	v_fmac_f32_e32 v25, v103, v35
	v_fmac_f32_e32 v18, v103, v39
	v_fmac_f32_e32 v19, v103, v43
	ds_read_b128 v[28:31], v2 offset:16592
	ds_read_b128 v[32:35], v2 offset:20688
	ds_read_b128 v[36:39], v2 offset:24784
	ds_read_b128 v[40:43], v2 offset:28880
	s_waitcnt lgkmcnt(8)
	v_fmac_f32_e32 v22, v100, v148
	v_fmac_f32_e32 v23, v100, v152
	v_fmac_f32_e32 v26, v100, v156
	v_fmac_f32_e32 v27, v100, v160
	v_fmac_f32_e32 v22, v101, v149
	v_fmac_f32_e32 v23, v101, v153
	v_fmac_f32_e32 v26, v101, v157
	v_fmac_f32_e32 v27, v101, v161
	v_fmac_f32_e32 v22, v102, v150
	v_fmac_f32_e32 v23, v102, v154
	v_fmac_f32_e32 v26, v102, v158
	v_fmac_f32_e32 v27, v102, v162
	v_fmac_f32_e32 v22, v103, v151
	v_fmac_f32_e32 v23, v103, v155
	v_fmac_f32_e32 v26, v103, v159
	v_fmac_f32_e32 v27, v103, v163
	ds_read_b128 v[148:151], v2 offset:32976
	ds_read_b128 v[152:155], v2 offset:37072
	ds_read_b128 v[156:159], v2 offset:41168
	ds_read_b128 v[160:163], v2 offset:45264
	s_waitcnt lgkmcnt(8)
	v_fmac_f32_e32 v12, v104, v164
	v_fmac_f32_e32 v13, v104, v168
	v_fmac_f32_e32 v14, v104, v172
	v_fmac_f32_e32 v15, v104, v176
	v_fmac_f32_e32 v12, v105, v165
	v_fmac_f32_e32 v13, v105, v169
	v_fmac_f32_e32 v14, v105, v173
	v_fmac_f32_e32 v15, v105, v177
	v_fmac_f32_e32 v12, v106, v166
	v_fmac_f32_e32 v13, v106, v170
	v_fmac_f32_e32 v14, v106, v174
	v_fmac_f32_e32 v15, v106, v178
	v_fmac_f32_e32 v12, v107, v167
	v_fmac_f32_e32 v13, v107, v171
	v_fmac_f32_e32 v14, v107, v175
	v_fmac_f32_e32 v15, v107, v179
	ds_read_b128 v[164:167], v2 offset:49360
	ds_read_b128 v[168:171], v2 offset:53456
	ds_read_b128 v[172:175], v2 offset:57552
	ds_read_b128 v[176:179], v2 offset:61648
	s_waitcnt lgkmcnt(8)
	v_fmac_f32_e32 v16, v104, v28
	v_fmac_f32_e32 v17, v104, v32
	v_fmac_f32_e32 v20, v104, v36
	v_fmac_f32_e32 v21, v104, v40
	v_fmac_f32_e32 v16, v105, v29
	v_fmac_f32_e32 v17, v105, v33
	v_fmac_f32_e32 v20, v105, v37
	v_fmac_f32_e32 v21, v105, v41
	v_fmac_f32_e32 v16, v106, v30
	v_fmac_f32_e32 v17, v106, v34
	v_fmac_f32_e32 v20, v106, v38
	v_fmac_f32_e32 v21, v106, v42
	v_fmac_f32_e32 v16, v107, v31
	v_fmac_f32_e32 v17, v107, v35
	v_fmac_f32_e32 v20, v107, v39
	v_fmac_f32_e32 v21, v107, v43
	ds_read_b128 v[28:31], v2 offset:224
	ds_read_b128 v[32:35], v2 offset:4320
	ds_read_b128 v[36:39], v2 offset:8416
	ds_read_b128 v[40:43], v2 offset:12512
	s_waitcnt lgkmcnt(8)
	v_fmac_f32_e32 v24, v104, v148
	v_fmac_f32_e32 v25, v104, v152
	v_fmac_f32_e32 v18, v104, v156
	v_fmac_f32_e32 v19, v104, v160
	v_fmac_f32_e32 v24, v105, v149
	v_fmac_f32_e32 v25, v105, v153
	v_fmac_f32_e32 v18, v105, v157
	v_fmac_f32_e32 v19, v105, v161
	v_fmac_f32_e32 v24, v106, v150
	v_fmac_f32_e32 v25, v106, v154
	v_fmac_f32_e32 v18, v106, v158
	v_fmac_f32_e32 v19, v106, v162
	v_fmac_f32_e32 v24, v107, v151
	v_fmac_f32_e32 v25, v107, v155
	v_fmac_f32_e32 v18, v107, v159
	v_fmac_f32_e32 v19, v107, v163
	ds_read_b128 v[148:151], v2 offset:16608
	ds_read_b128 v[152:155], v2 offset:20704
	ds_read_b128 v[156:159], v2 offset:24800
	ds_read_b128 v[160:163], v2 offset:28896
	s_waitcnt lgkmcnt(8)
	v_fmac_f32_e32 v22, v104, v164
	v_fmac_f32_e32 v23, v104, v168
	v_fmac_f32_e32 v26, v104, v172
	v_fmac_f32_e32 v27, v104, v176
	v_fmac_f32_e32 v22, v105, v165
	v_fmac_f32_e32 v23, v105, v169
	v_fmac_f32_e32 v26, v105, v173
	v_fmac_f32_e32 v27, v105, v177
	v_fmac_f32_e32 v22, v106, v166
	v_fmac_f32_e32 v23, v106, v170
	v_fmac_f32_e32 v26, v106, v174
	v_fmac_f32_e32 v27, v106, v178
	v_fmac_f32_e32 v22, v107, v167
	v_fmac_f32_e32 v23, v107, v171
	v_fmac_f32_e32 v26, v107, v175
	v_fmac_f32_e32 v27, v107, v179
	ds_read_b128 v[164:167], v2 offset:32992
	ds_read_b128 v[168:171], v2 offset:37088
	ds_read_b128 v[172:175], v2 offset:41184
	ds_read_b128 v[176:179], v2 offset:45280
	s_waitcnt lgkmcnt(8)
	v_fmac_f32_e32 v12, v108, v28
	v_fmac_f32_e32 v13, v108, v32
	v_fmac_f32_e32 v14, v108, v36
	v_fmac_f32_e32 v15, v108, v40
	v_fmac_f32_e32 v12, v109, v29
	v_fmac_f32_e32 v13, v109, v33
	v_fmac_f32_e32 v14, v109, v37
	v_fmac_f32_e32 v15, v109, v41
	v_fmac_f32_e32 v12, v110, v30
	v_fmac_f32_e32 v13, v110, v34
	v_fmac_f32_e32 v14, v110, v38
	v_fmac_f32_e32 v15, v110, v42
	v_fmac_f32_e32 v12, v111, v31
	v_fmac_f32_e32 v13, v111, v35
	v_fmac_f32_e32 v14, v111, v39
	v_fmac_f32_e32 v15, v111, v43
	ds_read_b128 v[28:31], v2 offset:49376
	ds_read_b128 v[32:35], v2 offset:53472
	ds_read_b128 v[36:39], v2 offset:57568
	ds_read_b128 v[40:43], v2 offset:61664
	s_waitcnt lgkmcnt(8)
	v_fmac_f32_e32 v16, v108, v148
	v_fmac_f32_e32 v17, v108, v152
	v_fmac_f32_e32 v20, v108, v156
	v_fmac_f32_e32 v21, v108, v160
	v_fmac_f32_e32 v16, v109, v149
	v_fmac_f32_e32 v17, v109, v153
	v_fmac_f32_e32 v20, v109, v157
	v_fmac_f32_e32 v21, v109, v161
	v_fmac_f32_e32 v16, v110, v150
	v_fmac_f32_e32 v17, v110, v154
	v_fmac_f32_e32 v20, v110, v158
	v_fmac_f32_e32 v21, v110, v162
	v_fmac_f32_e32 v16, v111, v151
	v_fmac_f32_e32 v17, v111, v155
	v_fmac_f32_e32 v20, v111, v159
	v_fmac_f32_e32 v21, v111, v163
	ds_read_b128 v[148:151], v2 offset:240
	ds_read_b128 v[152:155], v2 offset:4336
	ds_read_b128 v[156:159], v2 offset:8432
	ds_read_b128 v[160:163], v2 offset:12528
	s_waitcnt lgkmcnt(8)
	v_fmac_f32_e32 v24, v108, v164
	v_fmac_f32_e32 v25, v108, v168
	v_fmac_f32_e32 v18, v108, v172
	v_fmac_f32_e32 v19, v108, v176
	v_fmac_f32_e32 v24, v109, v165
	v_fmac_f32_e32 v25, v109, v169
	v_fmac_f32_e32 v18, v109, v173
	v_fmac_f32_e32 v19, v109, v177
	v_fmac_f32_e32 v24, v110, v166
	v_fmac_f32_e32 v25, v110, v170
	v_fmac_f32_e32 v18, v110, v174
	v_fmac_f32_e32 v19, v110, v178
	v_fmac_f32_e32 v24, v111, v167
	v_fmac_f32_e32 v25, v111, v171
	v_fmac_f32_e32 v18, v111, v175
	v_fmac_f32_e32 v19, v111, v179
	ds_read_b128 v[164:167], v2 offset:16624
	ds_read_b128 v[168:171], v2 offset:20720
	ds_read_b128 v[172:175], v2 offset:24816
	ds_read_b128 v[176:179], v2 offset:28912
	s_waitcnt lgkmcnt(8)
	v_fmac_f32_e32 v22, v108, v28
	v_fmac_f32_e32 v23, v108, v32
	v_fmac_f32_e32 v26, v108, v36
	v_fmac_f32_e32 v27, v108, v40
	v_fmac_f32_e32 v22, v109, v29
	v_fmac_f32_e32 v23, v109, v33
	v_fmac_f32_e32 v26, v109, v37
	v_fmac_f32_e32 v27, v109, v41
	v_fmac_f32_e32 v22, v110, v30
	v_fmac_f32_e32 v23, v110, v34
	v_fmac_f32_e32 v26, v110, v38
	v_fmac_f32_e32 v27, v110, v42
	v_fmac_f32_e32 v22, v111, v31
	v_fmac_f32_e32 v23, v111, v35
	v_fmac_f32_e32 v26, v111, v39
	v_fmac_f32_e32 v27, v111, v43
	ds_read_b128 v[28:31], v2 offset:33008
	ds_read_b128 v[32:35], v2 offset:37104
	ds_read_b128 v[36:39], v2 offset:41200
	ds_read_b128 v[40:43], v2 offset:45296
	s_waitcnt lgkmcnt(8)
	v_fmac_f32_e32 v12, v112, v148
	v_fmac_f32_e32 v13, v112, v152
	v_fmac_f32_e32 v14, v112, v156
	v_fmac_f32_e32 v15, v112, v160
	v_fmac_f32_e32 v12, v113, v149
	v_fmac_f32_e32 v13, v113, v153
	v_fmac_f32_e32 v14, v113, v157
	v_fmac_f32_e32 v15, v113, v161
	v_fmac_f32_e32 v12, v114, v150
	v_fmac_f32_e32 v13, v114, v154
	v_fmac_f32_e32 v14, v114, v158
	v_fmac_f32_e32 v15, v114, v162
	v_fmac_f32_e32 v12, v115, v151
	v_fmac_f32_e32 v13, v115, v155
	v_fmac_f32_e32 v14, v115, v159
	v_fmac_f32_e32 v15, v115, v163
	ds_read_b128 v[148:151], v2 offset:49392
	ds_read_b128 v[152:155], v2 offset:53488
	ds_read_b128 v[156:159], v2 offset:57584
	ds_read_b128 v[160:163], v2 offset:61680
	s_waitcnt lgkmcnt(8)
	v_fmac_f32_e32 v16, v112, v164
	v_fmac_f32_e32 v17, v112, v168
	v_fmac_f32_e32 v20, v112, v172
	v_fmac_f32_e32 v21, v112, v176
	v_fmac_f32_e32 v16, v113, v165
	v_fmac_f32_e32 v17, v113, v169
	v_fmac_f32_e32 v20, v113, v173
	v_fmac_f32_e32 v21, v113, v177
	v_fmac_f32_e32 v16, v114, v166
	v_fmac_f32_e32 v17, v114, v170
	v_fmac_f32_e32 v20, v114, v174
	v_fmac_f32_e32 v21, v114, v178
	v_fmac_f32_e32 v16, v115, v167
	v_fmac_f32_e32 v17, v115, v171
	v_fmac_f32_e32 v20, v115, v175
	v_fmac_f32_e32 v21, v115, v179
	ds_read_b128 v[164:167], v2 offset:256
	ds_read_b128 v[168:171], v2 offset:4352
	ds_read_b128 v[172:175], v2 offset:8448
	ds_read_b128 v[176:179], v2 offset:12544
	s_waitcnt lgkmcnt(8)
	v_fmac_f32_e32 v24, v112, v28
	v_fmac_f32_e32 v25, v112, v32
	v_fmac_f32_e32 v18, v112, v36
	v_fmac_f32_e32 v19, v112, v40
	v_fmac_f32_e32 v24, v113, v29
	v_fmac_f32_e32 v25, v113, v33
	v_fmac_f32_e32 v18, v113, v37
	v_fmac_f32_e32 v19, v113, v41
	v_fmac_f32_e32 v24, v114, v30
	v_fmac_f32_e32 v25, v114, v34
	v_fmac_f32_e32 v18, v114, v38
	v_fmac_f32_e32 v19, v114, v42
	v_fmac_f32_e32 v24, v115, v31
	v_fmac_f32_e32 v25, v115, v35
	v_fmac_f32_e32 v18, v115, v39
	v_fmac_f32_e32 v19, v115, v43
	ds_read_b128 v[28:31], v2 offset:16640
	ds_read_b128 v[32:35], v2 offset:20736
	ds_read_b128 v[36:39], v2 offset:24832
	ds_read_b128 v[40:43], v2 offset:28928
	s_waitcnt lgkmcnt(8)
	v_fmac_f32_e32 v22, v112, v148
	v_fmac_f32_e32 v23, v112, v152
	v_fmac_f32_e32 v26, v112, v156
	v_fmac_f32_e32 v27, v112, v160
	v_fmac_f32_e32 v22, v113, v149
	v_fmac_f32_e32 v23, v113, v153
	v_fmac_f32_e32 v26, v113, v157
	v_fmac_f32_e32 v27, v113, v161
	v_fmac_f32_e32 v22, v114, v150
	v_fmac_f32_e32 v23, v114, v154
	v_fmac_f32_e32 v26, v114, v158
	v_fmac_f32_e32 v27, v114, v162
	v_fmac_f32_e32 v22, v115, v151
	v_fmac_f32_e32 v23, v115, v155
	v_fmac_f32_e32 v26, v115, v159
	v_fmac_f32_e32 v27, v115, v163
	global_load_dword v100, v[0:1], off
	v_lshl_add_u64 v[0:1], v[0:1], 0, s[50:51]
	global_load_dword v101, v[0:1], off
	v_lshl_add_u64 v[0:1], v[0:1], 0, s[50:51]
	global_load_dword v102, v[0:1], off
	v_lshl_add_u64 v[0:1], v[0:1], 0, s[50:51]
	global_load_dword v103, v[0:1], off
	v_lshl_add_u64 v[0:1], v[0:1], 0, s[50:51]
	global_load_dword v104, v[0:1], off
	v_lshl_add_u64 v[0:1], v[0:1], 0, s[50:51]
	global_load_dword v105, v[0:1], off
	v_lshl_add_u64 v[0:1], v[0:1], 0, s[50:51]
	global_load_dword v106, v[0:1], off
	v_lshl_add_u64 v[0:1], v[0:1], 0, s[50:51]
	global_load_dword v107, v[0:1], off
	v_lshl_add_u64 v[0:1], v[0:1], 0, s[50:51]
	global_load_dword v108, v[0:1], off
	v_lshl_add_u64 v[0:1], v[0:1], 0, s[50:51]
	global_load_dword v109, v[0:1], off
	v_lshl_add_u64 v[0:1], v[0:1], 0, s[50:51]
	global_load_dword v110, v[0:1], off
	v_lshl_add_u64 v[0:1], v[0:1], 0, s[50:51]
	global_load_dword v111, v[0:1], off
	v_lshl_add_u64 v[0:1], v[0:1], 0, s[50:51]
	global_load_dword v112, v[0:1], off
	v_lshl_add_u64 v[0:1], v[0:1], 0, s[50:51]
	global_load_dword v113, v[0:1], off
	v_lshl_add_u64 v[0:1], v[0:1], 0, s[50:51]
	global_load_dword v114, v[0:1], off
	v_lshl_add_u64 v[0:1], v[0:1], 0, s[50:51]
	global_load_dword v115, v[0:1], off
	v_lshl_add_u64 v[0:1], v[0:1], 0, s[50:51]
	s_waitcnt vmcnt(32)
	ds_read_b128 v[148:151], v2 offset:33024
	ds_read_b128 v[152:155], v2 offset:37120
	ds_read_b128 v[156:159], v2 offset:41216
	ds_read_b128 v[160:163], v2 offset:45312
	s_waitcnt lgkmcnt(8)
	v_fmac_f32_e32 v12, v116, v164
	v_fmac_f32_e32 v13, v116, v168
	v_fmac_f32_e32 v14, v116, v172
	v_fmac_f32_e32 v15, v116, v176
	v_fmac_f32_e32 v12, v117, v165
	v_fmac_f32_e32 v13, v117, v169
	v_fmac_f32_e32 v14, v117, v173
	v_fmac_f32_e32 v15, v117, v177
	v_fmac_f32_e32 v12, v118, v166
	v_fmac_f32_e32 v13, v118, v170
	v_fmac_f32_e32 v14, v118, v174
	v_fmac_f32_e32 v15, v118, v178
	v_fmac_f32_e32 v12, v119, v167
	v_fmac_f32_e32 v13, v119, v171
	v_fmac_f32_e32 v14, v119, v175
	v_fmac_f32_e32 v15, v119, v179
	ds_read_b128 v[164:167], v2 offset:49408
	ds_read_b128 v[168:171], v2 offset:53504
	ds_read_b128 v[172:175], v2 offset:57600
	ds_read_b128 v[176:179], v2 offset:61696
	s_waitcnt lgkmcnt(8)
	v_fmac_f32_e32 v16, v116, v28
	v_fmac_f32_e32 v17, v116, v32
	v_fmac_f32_e32 v20, v116, v36
	v_fmac_f32_e32 v21, v116, v40
	v_fmac_f32_e32 v16, v117, v29
	v_fmac_f32_e32 v17, v117, v33
	v_fmac_f32_e32 v20, v117, v37
	v_fmac_f32_e32 v21, v117, v41
	v_fmac_f32_e32 v16, v118, v30
	v_fmac_f32_e32 v17, v118, v34
	v_fmac_f32_e32 v20, v118, v38
	v_fmac_f32_e32 v21, v118, v42
	v_fmac_f32_e32 v16, v119, v31
	v_fmac_f32_e32 v17, v119, v35
	v_fmac_f32_e32 v20, v119, v39
	v_fmac_f32_e32 v21, v119, v43
	ds_read_b128 v[28:31], v2 offset:272
	ds_read_b128 v[32:35], v2 offset:4368
	ds_read_b128 v[36:39], v2 offset:8464
	ds_read_b128 v[40:43], v2 offset:12560
	s_waitcnt lgkmcnt(8)
	v_fmac_f32_e32 v24, v116, v148
	v_fmac_f32_e32 v25, v116, v152
	v_fmac_f32_e32 v18, v116, v156
	v_fmac_f32_e32 v19, v116, v160
	v_fmac_f32_e32 v24, v117, v149
	v_fmac_f32_e32 v25, v117, v153
	v_fmac_f32_e32 v18, v117, v157
	v_fmac_f32_e32 v19, v117, v161
	v_fmac_f32_e32 v24, v118, v150
	v_fmac_f32_e32 v25, v118, v154
	v_fmac_f32_e32 v18, v118, v158
	v_fmac_f32_e32 v19, v118, v162
	v_fmac_f32_e32 v24, v119, v151
	v_fmac_f32_e32 v25, v119, v155
	v_fmac_f32_e32 v18, v119, v159
	v_fmac_f32_e32 v19, v119, v163
	ds_read_b128 v[148:151], v2 offset:16656
	ds_read_b128 v[152:155], v2 offset:20752
	ds_read_b128 v[156:159], v2 offset:24848
	ds_read_b128 v[160:163], v2 offset:28944
	s_waitcnt lgkmcnt(8)
	v_fmac_f32_e32 v22, v116, v164
	v_fmac_f32_e32 v23, v116, v168
	v_fmac_f32_e32 v26, v116, v172
	v_fmac_f32_e32 v27, v116, v176
	v_fmac_f32_e32 v22, v117, v165
	v_fmac_f32_e32 v23, v117, v169
	v_fmac_f32_e32 v26, v117, v173
	v_fmac_f32_e32 v27, v117, v177
	v_fmac_f32_e32 v22, v118, v166
	v_fmac_f32_e32 v23, v118, v170
	v_fmac_f32_e32 v26, v118, v174
	v_fmac_f32_e32 v27, v118, v178
	v_fmac_f32_e32 v22, v119, v167
	v_fmac_f32_e32 v23, v119, v171
	v_fmac_f32_e32 v26, v119, v175
	v_fmac_f32_e32 v27, v119, v179
	ds_read_b128 v[164:167], v2 offset:33040
	ds_read_b128 v[168:171], v2 offset:37136
	ds_read_b128 v[172:175], v2 offset:41232
	ds_read_b128 v[176:179], v2 offset:45328
	s_waitcnt lgkmcnt(8)
	v_fmac_f32_e32 v12, v120, v28
	v_fmac_f32_e32 v13, v120, v32
	v_fmac_f32_e32 v14, v120, v36
	v_fmac_f32_e32 v15, v120, v40
	v_fmac_f32_e32 v12, v121, v29
	v_fmac_f32_e32 v13, v121, v33
	v_fmac_f32_e32 v14, v121, v37
	v_fmac_f32_e32 v15, v121, v41
	v_fmac_f32_e32 v12, v122, v30
	v_fmac_f32_e32 v13, v122, v34
	v_fmac_f32_e32 v14, v122, v38
	v_fmac_f32_e32 v15, v122, v42
	v_fmac_f32_e32 v12, v123, v31
	v_fmac_f32_e32 v13, v123, v35
	v_fmac_f32_e32 v14, v123, v39
	v_fmac_f32_e32 v15, v123, v43
	ds_read_b128 v[28:31], v2 offset:49424
	ds_read_b128 v[32:35], v2 offset:53520
	ds_read_b128 v[36:39], v2 offset:57616
	ds_read_b128 v[40:43], v2 offset:61712
	s_waitcnt lgkmcnt(8)
	v_fmac_f32_e32 v16, v120, v148
	v_fmac_f32_e32 v17, v120, v152
	v_fmac_f32_e32 v20, v120, v156
	v_fmac_f32_e32 v21, v120, v160
	v_fmac_f32_e32 v16, v121, v149
	v_fmac_f32_e32 v17, v121, v153
	v_fmac_f32_e32 v20, v121, v157
	v_fmac_f32_e32 v21, v121, v161
	v_fmac_f32_e32 v16, v122, v150
	v_fmac_f32_e32 v17, v122, v154
	v_fmac_f32_e32 v20, v122, v158
	v_fmac_f32_e32 v21, v122, v162
	v_fmac_f32_e32 v16, v123, v151
	v_fmac_f32_e32 v17, v123, v155
	v_fmac_f32_e32 v20, v123, v159
	v_fmac_f32_e32 v21, v123, v163
	ds_read_b128 v[148:151], v2 offset:288
	ds_read_b128 v[152:155], v2 offset:4384
	ds_read_b128 v[156:159], v2 offset:8480
	ds_read_b128 v[160:163], v2 offset:12576
	s_waitcnt lgkmcnt(8)
	v_fmac_f32_e32 v24, v120, v164
	v_fmac_f32_e32 v25, v120, v168
	v_fmac_f32_e32 v18, v120, v172
	v_fmac_f32_e32 v19, v120, v176
	v_fmac_f32_e32 v24, v121, v165
	v_fmac_f32_e32 v25, v121, v169
	v_fmac_f32_e32 v18, v121, v173
	v_fmac_f32_e32 v19, v121, v177
	v_fmac_f32_e32 v24, v122, v166
	v_fmac_f32_e32 v25, v122, v170
	v_fmac_f32_e32 v18, v122, v174
	v_fmac_f32_e32 v19, v122, v178
	v_fmac_f32_e32 v24, v123, v167
	v_fmac_f32_e32 v25, v123, v171
	v_fmac_f32_e32 v18, v123, v175
	v_fmac_f32_e32 v19, v123, v179
	ds_read_b128 v[164:167], v2 offset:16672
	ds_read_b128 v[168:171], v2 offset:20768
	ds_read_b128 v[172:175], v2 offset:24864
	ds_read_b128 v[176:179], v2 offset:28960
	s_waitcnt lgkmcnt(8)
	v_fmac_f32_e32 v22, v120, v28
	v_fmac_f32_e32 v23, v120, v32
	v_fmac_f32_e32 v26, v120, v36
	v_fmac_f32_e32 v27, v120, v40
	v_fmac_f32_e32 v22, v121, v29
	v_fmac_f32_e32 v23, v121, v33
	v_fmac_f32_e32 v26, v121, v37
	v_fmac_f32_e32 v27, v121, v41
	v_fmac_f32_e32 v22, v122, v30
	v_fmac_f32_e32 v23, v122, v34
	v_fmac_f32_e32 v26, v122, v38
	v_fmac_f32_e32 v27, v122, v42
	v_fmac_f32_e32 v22, v123, v31
	v_fmac_f32_e32 v23, v123, v35
	v_fmac_f32_e32 v26, v123, v39
	v_fmac_f32_e32 v27, v123, v43
	ds_read_b128 v[28:31], v2 offset:33056
	ds_read_b128 v[32:35], v2 offset:37152
	ds_read_b128 v[36:39], v2 offset:41248
	ds_read_b128 v[40:43], v2 offset:45344
	s_waitcnt lgkmcnt(8)
	v_fmac_f32_e32 v12, v124, v148
	v_fmac_f32_e32 v13, v124, v152
	v_fmac_f32_e32 v14, v124, v156
	v_fmac_f32_e32 v15, v124, v160
	v_fmac_f32_e32 v12, v125, v149
	v_fmac_f32_e32 v13, v125, v153
	v_fmac_f32_e32 v14, v125, v157
	v_fmac_f32_e32 v15, v125, v161
	v_fmac_f32_e32 v12, v126, v150
	v_fmac_f32_e32 v13, v126, v154
	v_fmac_f32_e32 v14, v126, v158
	v_fmac_f32_e32 v15, v126, v162
	v_fmac_f32_e32 v12, v127, v151
	v_fmac_f32_e32 v13, v127, v155
	v_fmac_f32_e32 v14, v127, v159
	v_fmac_f32_e32 v15, v127, v163
	ds_read_b128 v[148:151], v2 offset:49440
	ds_read_b128 v[152:155], v2 offset:53536
	ds_read_b128 v[156:159], v2 offset:57632
	ds_read_b128 v[160:163], v2 offset:61728
	s_waitcnt lgkmcnt(8)
	v_fmac_f32_e32 v16, v124, v164
	v_fmac_f32_e32 v17, v124, v168
	v_fmac_f32_e32 v20, v124, v172
	v_fmac_f32_e32 v21, v124, v176
	v_fmac_f32_e32 v16, v125, v165
	v_fmac_f32_e32 v17, v125, v169
	v_fmac_f32_e32 v20, v125, v173
	v_fmac_f32_e32 v21, v125, v177
	v_fmac_f32_e32 v16, v126, v166
	v_fmac_f32_e32 v17, v126, v170
	v_fmac_f32_e32 v20, v126, v174
	v_fmac_f32_e32 v21, v126, v178
	v_fmac_f32_e32 v16, v127, v167
	v_fmac_f32_e32 v17, v127, v171
	v_fmac_f32_e32 v20, v127, v175
	v_fmac_f32_e32 v21, v127, v179
	ds_read_b128 v[164:167], v2 offset:304
	ds_read_b128 v[168:171], v2 offset:4400
	ds_read_b128 v[172:175], v2 offset:8496
	ds_read_b128 v[176:179], v2 offset:12592
	s_waitcnt lgkmcnt(8)
	v_fmac_f32_e32 v24, v124, v28
	v_fmac_f32_e32 v25, v124, v32
	v_fmac_f32_e32 v18, v124, v36
	v_fmac_f32_e32 v19, v124, v40
	v_fmac_f32_e32 v24, v125, v29
	v_fmac_f32_e32 v25, v125, v33
	v_fmac_f32_e32 v18, v125, v37
	v_fmac_f32_e32 v19, v125, v41
	v_fmac_f32_e32 v24, v126, v30
	v_fmac_f32_e32 v25, v126, v34
	v_fmac_f32_e32 v18, v126, v38
	v_fmac_f32_e32 v19, v126, v42
	v_fmac_f32_e32 v24, v127, v31
	v_fmac_f32_e32 v25, v127, v35
	v_fmac_f32_e32 v18, v127, v39
	v_fmac_f32_e32 v19, v127, v43
	ds_read_b128 v[28:31], v2 offset:16688
	ds_read_b128 v[32:35], v2 offset:20784
	ds_read_b128 v[36:39], v2 offset:24880
	ds_read_b128 v[40:43], v2 offset:28976
	s_waitcnt lgkmcnt(8)
	v_fmac_f32_e32 v22, v124, v148
	v_fmac_f32_e32 v23, v124, v152
	v_fmac_f32_e32 v26, v124, v156
	v_fmac_f32_e32 v27, v124, v160
	v_fmac_f32_e32 v22, v125, v149
	v_fmac_f32_e32 v23, v125, v153
	v_fmac_f32_e32 v26, v125, v157
	v_fmac_f32_e32 v27, v125, v161
	v_fmac_f32_e32 v22, v126, v150
	v_fmac_f32_e32 v23, v126, v154
	v_fmac_f32_e32 v26, v126, v158
	v_fmac_f32_e32 v27, v126, v162
	v_fmac_f32_e32 v22, v127, v151
	v_fmac_f32_e32 v23, v127, v155
	v_fmac_f32_e32 v26, v127, v159
	v_fmac_f32_e32 v27, v127, v163
	ds_read_b128 v[148:151], v2 offset:33072
	ds_read_b128 v[152:155], v2 offset:37168
	ds_read_b128 v[156:159], v2 offset:41264
	ds_read_b128 v[160:163], v2 offset:45360
	s_waitcnt lgkmcnt(8)
	v_fmac_f32_e32 v12, v128, v164
	v_fmac_f32_e32 v13, v128, v168
	v_fmac_f32_e32 v14, v128, v172
	v_fmac_f32_e32 v15, v128, v176
	v_fmac_f32_e32 v12, v129, v165
	v_fmac_f32_e32 v13, v129, v169
	v_fmac_f32_e32 v14, v129, v173
	v_fmac_f32_e32 v15, v129, v177
	v_fmac_f32_e32 v12, v130, v166
	v_fmac_f32_e32 v13, v130, v170
	v_fmac_f32_e32 v14, v130, v174
	v_fmac_f32_e32 v15, v130, v178
	v_fmac_f32_e32 v12, v131, v167
	v_fmac_f32_e32 v13, v131, v171
	v_fmac_f32_e32 v14, v131, v175
	v_fmac_f32_e32 v15, v131, v179
	ds_read_b128 v[164:167], v2 offset:49456
	ds_read_b128 v[168:171], v2 offset:53552
	ds_read_b128 v[172:175], v2 offset:57648
	ds_read_b128 v[176:179], v2 offset:61744
	s_waitcnt lgkmcnt(8)
	v_fmac_f32_e32 v16, v128, v28
	v_fmac_f32_e32 v17, v128, v32
	v_fmac_f32_e32 v20, v128, v36
	v_fmac_f32_e32 v21, v128, v40
	v_fmac_f32_e32 v16, v129, v29
	v_fmac_f32_e32 v17, v129, v33
	v_fmac_f32_e32 v20, v129, v37
	v_fmac_f32_e32 v21, v129, v41
	v_fmac_f32_e32 v16, v130, v30
	v_fmac_f32_e32 v17, v130, v34
	v_fmac_f32_e32 v20, v130, v38
	v_fmac_f32_e32 v21, v130, v42
	v_fmac_f32_e32 v16, v131, v31
	v_fmac_f32_e32 v17, v131, v35
	v_fmac_f32_e32 v20, v131, v39
	v_fmac_f32_e32 v21, v131, v43
	ds_read_b128 v[28:31], v2 offset:320
	ds_read_b128 v[32:35], v2 offset:4416
	ds_read_b128 v[36:39], v2 offset:8512
	ds_read_b128 v[40:43], v2 offset:12608
	s_waitcnt lgkmcnt(8)
	v_fmac_f32_e32 v24, v128, v148
	v_fmac_f32_e32 v25, v128, v152
	v_fmac_f32_e32 v18, v128, v156
	v_fmac_f32_e32 v19, v128, v160
	v_fmac_f32_e32 v24, v129, v149
	v_fmac_f32_e32 v25, v129, v153
	v_fmac_f32_e32 v18, v129, v157
	v_fmac_f32_e32 v19, v129, v161
	v_fmac_f32_e32 v24, v130, v150
	v_fmac_f32_e32 v25, v130, v154
	v_fmac_f32_e32 v18, v130, v158
	v_fmac_f32_e32 v19, v130, v162
	v_fmac_f32_e32 v24, v131, v151
	v_fmac_f32_e32 v25, v131, v155
	v_fmac_f32_e32 v18, v131, v159
	v_fmac_f32_e32 v19, v131, v163
	ds_read_b128 v[148:151], v2 offset:16704
	ds_read_b128 v[152:155], v2 offset:20800
	ds_read_b128 v[156:159], v2 offset:24896
	ds_read_b128 v[160:163], v2 offset:28992
	s_waitcnt lgkmcnt(8)
	v_fmac_f32_e32 v22, v128, v164
	v_fmac_f32_e32 v23, v128, v168
	v_fmac_f32_e32 v26, v128, v172
	v_fmac_f32_e32 v27, v128, v176
	v_fmac_f32_e32 v22, v129, v165
	v_fmac_f32_e32 v23, v129, v169
	v_fmac_f32_e32 v26, v129, v173
	v_fmac_f32_e32 v27, v129, v177
	v_fmac_f32_e32 v22, v130, v166
	v_fmac_f32_e32 v23, v130, v170
	v_fmac_f32_e32 v26, v130, v174
	v_fmac_f32_e32 v27, v130, v178
	v_fmac_f32_e32 v22, v131, v167
	v_fmac_f32_e32 v23, v131, v171
	v_fmac_f32_e32 v26, v131, v175
	v_fmac_f32_e32 v27, v131, v179
	global_load_dword v116, v[0:1], off
	v_lshl_add_u64 v[0:1], v[0:1], 0, s[50:51]
	global_load_dword v117, v[0:1], off
	v_lshl_add_u64 v[0:1], v[0:1], 0, s[50:51]
	global_load_dword v118, v[0:1], off
	v_lshl_add_u64 v[0:1], v[0:1], 0, s[50:51]
	global_load_dword v119, v[0:1], off
	v_lshl_add_u64 v[0:1], v[0:1], 0, s[50:51]
	global_load_dword v120, v[0:1], off
	v_lshl_add_u64 v[0:1], v[0:1], 0, s[50:51]
	global_load_dword v121, v[0:1], off
	v_lshl_add_u64 v[0:1], v[0:1], 0, s[50:51]
	global_load_dword v122, v[0:1], off
	v_lshl_add_u64 v[0:1], v[0:1], 0, s[50:51]
	global_load_dword v123, v[0:1], off
	v_lshl_add_u64 v[0:1], v[0:1], 0, s[50:51]
	global_load_dword v124, v[0:1], off
	v_lshl_add_u64 v[0:1], v[0:1], 0, s[50:51]
	global_load_dword v125, v[0:1], off
	v_lshl_add_u64 v[0:1], v[0:1], 0, s[50:51]
	global_load_dword v126, v[0:1], off
	v_lshl_add_u64 v[0:1], v[0:1], 0, s[50:51]
	global_load_dword v127, v[0:1], off
	v_lshl_add_u64 v[0:1], v[0:1], 0, s[50:51]
	global_load_dword v128, v[0:1], off
	v_lshl_add_u64 v[0:1], v[0:1], 0, s[50:51]
	global_load_dword v129, v[0:1], off
	v_lshl_add_u64 v[0:1], v[0:1], 0, s[50:51]
	global_load_dword v130, v[0:1], off
	v_lshl_add_u64 v[0:1], v[0:1], 0, s[50:51]
	global_load_dword v131, v[0:1], off
	v_lshl_add_u64 v[0:1], v[0:1], 0, s[50:51]
	s_waitcnt vmcnt(32)
	ds_read_b128 v[164:167], v2 offset:33088
	ds_read_b128 v[168:171], v2 offset:37184
	ds_read_b128 v[172:175], v2 offset:41280
	ds_read_b128 v[176:179], v2 offset:45376
	s_waitcnt lgkmcnt(8)
	v_fmac_f32_e32 v12, v132, v28
	v_fmac_f32_e32 v13, v132, v32
	v_fmac_f32_e32 v14, v132, v36
	v_fmac_f32_e32 v15, v132, v40
	v_fmac_f32_e32 v12, v133, v29
	v_fmac_f32_e32 v13, v133, v33
	v_fmac_f32_e32 v14, v133, v37
	v_fmac_f32_e32 v15, v133, v41
	v_fmac_f32_e32 v12, v134, v30
	v_fmac_f32_e32 v13, v134, v34
	v_fmac_f32_e32 v14, v134, v38
	v_fmac_f32_e32 v15, v134, v42
	v_fmac_f32_e32 v12, v135, v31
	v_fmac_f32_e32 v13, v135, v35
	v_fmac_f32_e32 v14, v135, v39
	v_fmac_f32_e32 v15, v135, v43
	ds_read_b128 v[28:31], v2 offset:49472
	ds_read_b128 v[32:35], v2 offset:53568
	ds_read_b128 v[36:39], v2 offset:57664
	ds_read_b128 v[40:43], v2 offset:61760
	s_waitcnt lgkmcnt(8)
	v_fmac_f32_e32 v16, v132, v148
	v_fmac_f32_e32 v17, v132, v152
	v_fmac_f32_e32 v20, v132, v156
	v_fmac_f32_e32 v21, v132, v160
	v_fmac_f32_e32 v16, v133, v149
	v_fmac_f32_e32 v17, v133, v153
	v_fmac_f32_e32 v20, v133, v157
	v_fmac_f32_e32 v21, v133, v161
	v_fmac_f32_e32 v16, v134, v150
	v_fmac_f32_e32 v17, v134, v154
	v_fmac_f32_e32 v20, v134, v158
	v_fmac_f32_e32 v21, v134, v162
	v_fmac_f32_e32 v16, v135, v151
	v_fmac_f32_e32 v17, v135, v155
	v_fmac_f32_e32 v20, v135, v159
	v_fmac_f32_e32 v21, v135, v163
	ds_read_b128 v[148:151], v2 offset:336
	ds_read_b128 v[152:155], v2 offset:4432
	ds_read_b128 v[156:159], v2 offset:8528
	ds_read_b128 v[160:163], v2 offset:12624
	s_waitcnt lgkmcnt(8)
	v_fmac_f32_e32 v24, v132, v164
	v_fmac_f32_e32 v25, v132, v168
	v_fmac_f32_e32 v18, v132, v172
	v_fmac_f32_e32 v19, v132, v176
	v_fmac_f32_e32 v24, v133, v165
	v_fmac_f32_e32 v25, v133, v169
	v_fmac_f32_e32 v18, v133, v173
	v_fmac_f32_e32 v19, v133, v177
	v_fmac_f32_e32 v24, v134, v166
	v_fmac_f32_e32 v25, v134, v170
	v_fmac_f32_e32 v18, v134, v174
	v_fmac_f32_e32 v19, v134, v178
	v_fmac_f32_e32 v24, v135, v167
	v_fmac_f32_e32 v25, v135, v171
	v_fmac_f32_e32 v18, v135, v175
	v_fmac_f32_e32 v19, v135, v179
	ds_read_b128 v[164:167], v2 offset:16720
	ds_read_b128 v[168:171], v2 offset:20816
	ds_read_b128 v[172:175], v2 offset:24912
	ds_read_b128 v[176:179], v2 offset:29008
	s_waitcnt lgkmcnt(8)
	v_fmac_f32_e32 v22, v132, v28
	v_fmac_f32_e32 v23, v132, v32
	v_fmac_f32_e32 v26, v132, v36
	v_fmac_f32_e32 v27, v132, v40
	v_fmac_f32_e32 v22, v133, v29
	v_fmac_f32_e32 v23, v133, v33
	v_fmac_f32_e32 v26, v133, v37
	v_fmac_f32_e32 v27, v133, v41
	v_fmac_f32_e32 v22, v134, v30
	v_fmac_f32_e32 v23, v134, v34
	v_fmac_f32_e32 v26, v134, v38
	v_fmac_f32_e32 v27, v134, v42
	v_fmac_f32_e32 v22, v135, v31
	v_fmac_f32_e32 v23, v135, v35
	v_fmac_f32_e32 v26, v135, v39
	v_fmac_f32_e32 v27, v135, v43
	ds_read_b128 v[28:31], v2 offset:33104
	ds_read_b128 v[32:35], v2 offset:37200
	ds_read_b128 v[36:39], v2 offset:41296
	ds_read_b128 v[40:43], v2 offset:45392
	s_waitcnt lgkmcnt(8)
	v_fmac_f32_e32 v12, v136, v148
	v_fmac_f32_e32 v13, v136, v152
	v_fmac_f32_e32 v14, v136, v156
	v_fmac_f32_e32 v15, v136, v160
	v_fmac_f32_e32 v12, v137, v149
	v_fmac_f32_e32 v13, v137, v153
	v_fmac_f32_e32 v14, v137, v157
	v_fmac_f32_e32 v15, v137, v161
	v_fmac_f32_e32 v12, v138, v150
	v_fmac_f32_e32 v13, v138, v154
	v_fmac_f32_e32 v14, v138, v158
	v_fmac_f32_e32 v15, v138, v162
	v_fmac_f32_e32 v12, v139, v151
	v_fmac_f32_e32 v13, v139, v155
	v_fmac_f32_e32 v14, v139, v159
	v_fmac_f32_e32 v15, v139, v163
	ds_read_b128 v[148:151], v2 offset:49488
	ds_read_b128 v[152:155], v2 offset:53584
	ds_read_b128 v[156:159], v2 offset:57680
	ds_read_b128 v[160:163], v2 offset:61776
	s_waitcnt lgkmcnt(8)
	v_fmac_f32_e32 v16, v136, v164
	v_fmac_f32_e32 v17, v136, v168
	v_fmac_f32_e32 v20, v136, v172
	v_fmac_f32_e32 v21, v136, v176
	v_fmac_f32_e32 v16, v137, v165
	v_fmac_f32_e32 v17, v137, v169
	v_fmac_f32_e32 v20, v137, v173
	v_fmac_f32_e32 v21, v137, v177
	v_fmac_f32_e32 v16, v138, v166
	v_fmac_f32_e32 v17, v138, v170
	v_fmac_f32_e32 v20, v138, v174
	v_fmac_f32_e32 v21, v138, v178
	v_fmac_f32_e32 v16, v139, v167
	v_fmac_f32_e32 v17, v139, v171
	v_fmac_f32_e32 v20, v139, v175
	v_fmac_f32_e32 v21, v139, v179
	ds_read_b128 v[164:167], v2 offset:352
	ds_read_b128 v[168:171], v2 offset:4448
	ds_read_b128 v[172:175], v2 offset:8544
	ds_read_b128 v[176:179], v2 offset:12640
	s_waitcnt lgkmcnt(8)
	v_fmac_f32_e32 v24, v136, v28
	v_fmac_f32_e32 v25, v136, v32
	v_fmac_f32_e32 v18, v136, v36
	v_fmac_f32_e32 v19, v136, v40
	v_fmac_f32_e32 v24, v137, v29
	v_fmac_f32_e32 v25, v137, v33
	v_fmac_f32_e32 v18, v137, v37
	v_fmac_f32_e32 v19, v137, v41
	v_fmac_f32_e32 v24, v138, v30
	v_fmac_f32_e32 v25, v138, v34
	v_fmac_f32_e32 v18, v138, v38
	v_fmac_f32_e32 v19, v138, v42
	v_fmac_f32_e32 v24, v139, v31
	v_fmac_f32_e32 v25, v139, v35
	v_fmac_f32_e32 v18, v139, v39
	v_fmac_f32_e32 v19, v139, v43
	ds_read_b128 v[28:31], v2 offset:16736
	ds_read_b128 v[32:35], v2 offset:20832
	ds_read_b128 v[36:39], v2 offset:24928
	ds_read_b128 v[40:43], v2 offset:29024
	s_waitcnt lgkmcnt(8)
	v_fmac_f32_e32 v22, v136, v148
	v_fmac_f32_e32 v23, v136, v152
	v_fmac_f32_e32 v26, v136, v156
	v_fmac_f32_e32 v27, v136, v160
	v_fmac_f32_e32 v22, v137, v149
	v_fmac_f32_e32 v23, v137, v153
	v_fmac_f32_e32 v26, v137, v157
	v_fmac_f32_e32 v27, v137, v161
	v_fmac_f32_e32 v22, v138, v150
	v_fmac_f32_e32 v23, v138, v154
	v_fmac_f32_e32 v26, v138, v158
	v_fmac_f32_e32 v27, v138, v162
	v_fmac_f32_e32 v22, v139, v151
	v_fmac_f32_e32 v23, v139, v155
	v_fmac_f32_e32 v26, v139, v159
	v_fmac_f32_e32 v27, v139, v163
	ds_read_b128 v[148:151], v2 offset:33120
	ds_read_b128 v[152:155], v2 offset:37216
	ds_read_b128 v[156:159], v2 offset:41312
	ds_read_b128 v[160:163], v2 offset:45408
	s_waitcnt lgkmcnt(8)
	v_fmac_f32_e32 v12, v140, v164
	v_fmac_f32_e32 v13, v140, v168
	v_fmac_f32_e32 v14, v140, v172
	v_fmac_f32_e32 v15, v140, v176
	v_fmac_f32_e32 v12, v141, v165
	v_fmac_f32_e32 v13, v141, v169
	v_fmac_f32_e32 v14, v141, v173
	v_fmac_f32_e32 v15, v141, v177
	v_fmac_f32_e32 v12, v142, v166
	v_fmac_f32_e32 v13, v142, v170
	v_fmac_f32_e32 v14, v142, v174
	v_fmac_f32_e32 v15, v142, v178
	v_fmac_f32_e32 v12, v143, v167
	v_fmac_f32_e32 v13, v143, v171
	v_fmac_f32_e32 v14, v143, v175
	v_fmac_f32_e32 v15, v143, v179
	ds_read_b128 v[164:167], v2 offset:49504
	ds_read_b128 v[168:171], v2 offset:53600
	ds_read_b128 v[172:175], v2 offset:57696
	ds_read_b128 v[176:179], v2 offset:61792
	s_waitcnt lgkmcnt(8)
	v_fmac_f32_e32 v16, v140, v28
	v_fmac_f32_e32 v17, v140, v32
	v_fmac_f32_e32 v20, v140, v36
	v_fmac_f32_e32 v21, v140, v40
	v_fmac_f32_e32 v16, v141, v29
	v_fmac_f32_e32 v17, v141, v33
	v_fmac_f32_e32 v20, v141, v37
	v_fmac_f32_e32 v21, v141, v41
	v_fmac_f32_e32 v16, v142, v30
	v_fmac_f32_e32 v17, v142, v34
	v_fmac_f32_e32 v20, v142, v38
	v_fmac_f32_e32 v21, v142, v42
	v_fmac_f32_e32 v16, v143, v31
	v_fmac_f32_e32 v17, v143, v35
	v_fmac_f32_e32 v20, v143, v39
	v_fmac_f32_e32 v21, v143, v43
	ds_read_b128 v[28:31], v2 offset:368
	ds_read_b128 v[32:35], v2 offset:4464
	ds_read_b128 v[36:39], v2 offset:8560
	ds_read_b128 v[40:43], v2 offset:12656
	s_waitcnt lgkmcnt(8)
	v_fmac_f32_e32 v24, v140, v148
	v_fmac_f32_e32 v25, v140, v152
	v_fmac_f32_e32 v18, v140, v156
	v_fmac_f32_e32 v19, v140, v160
	v_fmac_f32_e32 v24, v141, v149
	v_fmac_f32_e32 v25, v141, v153
	v_fmac_f32_e32 v18, v141, v157
	v_fmac_f32_e32 v19, v141, v161
	v_fmac_f32_e32 v24, v142, v150
	v_fmac_f32_e32 v25, v142, v154
	v_fmac_f32_e32 v18, v142, v158
	v_fmac_f32_e32 v19, v142, v162
	v_fmac_f32_e32 v24, v143, v151
	v_fmac_f32_e32 v25, v143, v155
	v_fmac_f32_e32 v18, v143, v159
	v_fmac_f32_e32 v19, v143, v163
	ds_read_b128 v[148:151], v2 offset:16752
	ds_read_b128 v[152:155], v2 offset:20848
	ds_read_b128 v[156:159], v2 offset:24944
	ds_read_b128 v[160:163], v2 offset:29040
	s_waitcnt lgkmcnt(8)
	v_fmac_f32_e32 v22, v140, v164
	v_fmac_f32_e32 v23, v140, v168
	v_fmac_f32_e32 v26, v140, v172
	v_fmac_f32_e32 v27, v140, v176
	v_fmac_f32_e32 v22, v141, v165
	v_fmac_f32_e32 v23, v141, v169
	v_fmac_f32_e32 v26, v141, v173
	v_fmac_f32_e32 v27, v141, v177
	v_fmac_f32_e32 v22, v142, v166
	v_fmac_f32_e32 v23, v142, v170
	v_fmac_f32_e32 v26, v142, v174
	v_fmac_f32_e32 v27, v142, v178
	v_fmac_f32_e32 v22, v143, v167
	v_fmac_f32_e32 v23, v143, v171
	v_fmac_f32_e32 v26, v143, v175
	v_fmac_f32_e32 v27, v143, v179
	ds_read_b128 v[164:167], v2 offset:33136
	ds_read_b128 v[168:171], v2 offset:37232
	ds_read_b128 v[172:175], v2 offset:41328
	ds_read_b128 v[176:179], v2 offset:45424
	s_waitcnt lgkmcnt(8)
	v_fmac_f32_e32 v12, v144, v28
	v_fmac_f32_e32 v13, v144, v32
	v_fmac_f32_e32 v14, v144, v36
	v_fmac_f32_e32 v15, v144, v40
	v_fmac_f32_e32 v12, v145, v29
	v_fmac_f32_e32 v13, v145, v33
	v_fmac_f32_e32 v14, v145, v37
	v_fmac_f32_e32 v15, v145, v41
	v_fmac_f32_e32 v12, v146, v30
	v_fmac_f32_e32 v13, v146, v34
	v_fmac_f32_e32 v14, v146, v38
	v_fmac_f32_e32 v15, v146, v42
	v_fmac_f32_e32 v12, v147, v31
	v_fmac_f32_e32 v13, v147, v35
	v_fmac_f32_e32 v14, v147, v39
	v_fmac_f32_e32 v15, v147, v43
	ds_read_b128 v[28:31], v2 offset:49520
	ds_read_b128 v[32:35], v2 offset:53616
	ds_read_b128 v[36:39], v2 offset:57712
	ds_read_b128 v[40:43], v2 offset:61808
	s_waitcnt lgkmcnt(8)
	v_fmac_f32_e32 v16, v144, v148
	v_fmac_f32_e32 v17, v144, v152
	v_fmac_f32_e32 v20, v144, v156
	v_fmac_f32_e32 v21, v144, v160
	v_fmac_f32_e32 v16, v145, v149
	v_fmac_f32_e32 v17, v145, v153
	v_fmac_f32_e32 v20, v145, v157
	v_fmac_f32_e32 v21, v145, v161
	v_fmac_f32_e32 v16, v146, v150
	v_fmac_f32_e32 v17, v146, v154
	v_fmac_f32_e32 v20, v146, v158
	v_fmac_f32_e32 v21, v146, v162
	v_fmac_f32_e32 v16, v147, v151
	v_fmac_f32_e32 v17, v147, v155
	v_fmac_f32_e32 v20, v147, v159
	v_fmac_f32_e32 v21, v147, v163
	ds_read_b128 v[148:151], v2 offset:384
	ds_read_b128 v[152:155], v2 offset:4480
	ds_read_b128 v[156:159], v2 offset:8576
	ds_read_b128 v[160:163], v2 offset:12672
	s_waitcnt lgkmcnt(8)
	v_fmac_f32_e32 v24, v144, v164
	v_fmac_f32_e32 v25, v144, v168
	v_fmac_f32_e32 v18, v144, v172
	v_fmac_f32_e32 v19, v144, v176
	v_fmac_f32_e32 v24, v145, v165
	v_fmac_f32_e32 v25, v145, v169
	v_fmac_f32_e32 v18, v145, v173
	v_fmac_f32_e32 v19, v145, v177
	v_fmac_f32_e32 v24, v146, v166
	v_fmac_f32_e32 v25, v146, v170
	v_fmac_f32_e32 v18, v146, v174
	v_fmac_f32_e32 v19, v146, v178
	v_fmac_f32_e32 v24, v147, v167
	v_fmac_f32_e32 v25, v147, v171
	v_fmac_f32_e32 v18, v147, v175
	v_fmac_f32_e32 v19, v147, v179
	ds_read_b128 v[164:167], v2 offset:16768
	ds_read_b128 v[168:171], v2 offset:20864
	ds_read_b128 v[172:175], v2 offset:24960
	ds_read_b128 v[176:179], v2 offset:29056
	s_waitcnt lgkmcnt(8)
	v_fmac_f32_e32 v22, v144, v28
	v_fmac_f32_e32 v23, v144, v32
	v_fmac_f32_e32 v26, v144, v36
	v_fmac_f32_e32 v27, v144, v40
	v_fmac_f32_e32 v22, v145, v29
	v_fmac_f32_e32 v23, v145, v33
	v_fmac_f32_e32 v26, v145, v37
	v_fmac_f32_e32 v27, v145, v41
	v_fmac_f32_e32 v22, v146, v30
	v_fmac_f32_e32 v23, v146, v34
	v_fmac_f32_e32 v26, v146, v38
	v_fmac_f32_e32 v27, v146, v42
	v_fmac_f32_e32 v22, v147, v31
	v_fmac_f32_e32 v23, v147, v35
	v_fmac_f32_e32 v26, v147, v39
	v_fmac_f32_e32 v27, v147, v43
	s_waitcnt vmcnt(16)
	ds_read_b128 v[28:31], v2 offset:33152
	ds_read_b128 v[32:35], v2 offset:37248
	ds_read_b128 v[36:39], v2 offset:41344
	ds_read_b128 v[40:43], v2 offset:45440
	s_waitcnt lgkmcnt(8)
	v_fmac_f32_e32 v12, v100, v148
	v_fmac_f32_e32 v13, v100, v152
	v_fmac_f32_e32 v14, v100, v156
	v_fmac_f32_e32 v15, v100, v160
	v_fmac_f32_e32 v12, v101, v149
	v_fmac_f32_e32 v13, v101, v153
	v_fmac_f32_e32 v14, v101, v157
	v_fmac_f32_e32 v15, v101, v161
	v_fmac_f32_e32 v12, v102, v150
	v_fmac_f32_e32 v13, v102, v154
	v_fmac_f32_e32 v14, v102, v158
	v_fmac_f32_e32 v15, v102, v162
	v_fmac_f32_e32 v12, v103, v151
	v_fmac_f32_e32 v13, v103, v155
	v_fmac_f32_e32 v14, v103, v159
	v_fmac_f32_e32 v15, v103, v163
	ds_read_b128 v[148:151], v2 offset:49536
	ds_read_b128 v[152:155], v2 offset:53632
	ds_read_b128 v[156:159], v2 offset:57728
	ds_read_b128 v[160:163], v2 offset:61824
	s_waitcnt lgkmcnt(8)
	v_fmac_f32_e32 v16, v100, v164
	v_fmac_f32_e32 v17, v100, v168
	v_fmac_f32_e32 v20, v100, v172
	v_fmac_f32_e32 v21, v100, v176
	v_fmac_f32_e32 v16, v101, v165
	v_fmac_f32_e32 v17, v101, v169
	v_fmac_f32_e32 v20, v101, v173
	v_fmac_f32_e32 v21, v101, v177
	v_fmac_f32_e32 v16, v102, v166
	v_fmac_f32_e32 v17, v102, v170
	v_fmac_f32_e32 v20, v102, v174
	v_fmac_f32_e32 v21, v102, v178
	v_fmac_f32_e32 v16, v103, v167
	v_fmac_f32_e32 v17, v103, v171
	v_fmac_f32_e32 v20, v103, v175
	v_fmac_f32_e32 v21, v103, v179
	ds_read_b128 v[164:167], v2 offset:400
	ds_read_b128 v[168:171], v2 offset:4496
	ds_read_b128 v[172:175], v2 offset:8592
	ds_read_b128 v[176:179], v2 offset:12688
	s_waitcnt lgkmcnt(8)
	v_fmac_f32_e32 v24, v100, v28
	v_fmac_f32_e32 v25, v100, v32
	v_fmac_f32_e32 v18, v100, v36
	v_fmac_f32_e32 v19, v100, v40
	v_fmac_f32_e32 v24, v101, v29
	v_fmac_f32_e32 v25, v101, v33
	v_fmac_f32_e32 v18, v101, v37
	v_fmac_f32_e32 v19, v101, v41
	v_fmac_f32_e32 v24, v102, v30
	v_fmac_f32_e32 v25, v102, v34
	v_fmac_f32_e32 v18, v102, v38
	v_fmac_f32_e32 v19, v102, v42
	v_fmac_f32_e32 v24, v103, v31
	v_fmac_f32_e32 v25, v103, v35
	v_fmac_f32_e32 v18, v103, v39
	v_fmac_f32_e32 v19, v103, v43
	ds_read_b128 v[28:31], v2 offset:16784
	ds_read_b128 v[32:35], v2 offset:20880
	ds_read_b128 v[36:39], v2 offset:24976
	ds_read_b128 v[40:43], v2 offset:29072
	s_waitcnt lgkmcnt(8)
	v_fmac_f32_e32 v22, v100, v148
	v_fmac_f32_e32 v23, v100, v152
	v_fmac_f32_e32 v26, v100, v156
	v_fmac_f32_e32 v27, v100, v160
	v_fmac_f32_e32 v22, v101, v149
	v_fmac_f32_e32 v23, v101, v153
	v_fmac_f32_e32 v26, v101, v157
	v_fmac_f32_e32 v27, v101, v161
	v_fmac_f32_e32 v22, v102, v150
	v_fmac_f32_e32 v23, v102, v154
	v_fmac_f32_e32 v26, v102, v158
	v_fmac_f32_e32 v27, v102, v162
	v_fmac_f32_e32 v22, v103, v151
	v_fmac_f32_e32 v23, v103, v155
	v_fmac_f32_e32 v26, v103, v159
	v_fmac_f32_e32 v27, v103, v163
	ds_read_b128 v[148:151], v2 offset:33168
	ds_read_b128 v[152:155], v2 offset:37264
	ds_read_b128 v[156:159], v2 offset:41360
	ds_read_b128 v[160:163], v2 offset:45456
	s_waitcnt lgkmcnt(8)
	v_fmac_f32_e32 v12, v104, v164
	v_fmac_f32_e32 v13, v104, v168
	v_fmac_f32_e32 v14, v104, v172
	v_fmac_f32_e32 v15, v104, v176
	v_fmac_f32_e32 v12, v105, v165
	v_fmac_f32_e32 v13, v105, v169
	v_fmac_f32_e32 v14, v105, v173
	v_fmac_f32_e32 v15, v105, v177
	v_fmac_f32_e32 v12, v106, v166
	v_fmac_f32_e32 v13, v106, v170
	v_fmac_f32_e32 v14, v106, v174
	v_fmac_f32_e32 v15, v106, v178
	v_fmac_f32_e32 v12, v107, v167
	v_fmac_f32_e32 v13, v107, v171
	v_fmac_f32_e32 v14, v107, v175
	v_fmac_f32_e32 v15, v107, v179
	ds_read_b128 v[164:167], v2 offset:49552
	ds_read_b128 v[168:171], v2 offset:53648
	ds_read_b128 v[172:175], v2 offset:57744
	ds_read_b128 v[176:179], v2 offset:61840
	s_waitcnt lgkmcnt(8)
	v_fmac_f32_e32 v16, v104, v28
	v_fmac_f32_e32 v17, v104, v32
	v_fmac_f32_e32 v20, v104, v36
	v_fmac_f32_e32 v21, v104, v40
	v_fmac_f32_e32 v16, v105, v29
	v_fmac_f32_e32 v17, v105, v33
	v_fmac_f32_e32 v20, v105, v37
	v_fmac_f32_e32 v21, v105, v41
	v_fmac_f32_e32 v16, v106, v30
	v_fmac_f32_e32 v17, v106, v34
	v_fmac_f32_e32 v20, v106, v38
	v_fmac_f32_e32 v21, v106, v42
	v_fmac_f32_e32 v16, v107, v31
	v_fmac_f32_e32 v17, v107, v35
	v_fmac_f32_e32 v20, v107, v39
	v_fmac_f32_e32 v21, v107, v43
	ds_read_b128 v[28:31], v2 offset:416
	ds_read_b128 v[32:35], v2 offset:4512
	ds_read_b128 v[36:39], v2 offset:8608
	ds_read_b128 v[40:43], v2 offset:12704
	s_waitcnt lgkmcnt(8)
	v_fmac_f32_e32 v24, v104, v148
	v_fmac_f32_e32 v25, v104, v152
	v_fmac_f32_e32 v18, v104, v156
	v_fmac_f32_e32 v19, v104, v160
	v_fmac_f32_e32 v24, v105, v149
	v_fmac_f32_e32 v25, v105, v153
	v_fmac_f32_e32 v18, v105, v157
	v_fmac_f32_e32 v19, v105, v161
	v_fmac_f32_e32 v24, v106, v150
	v_fmac_f32_e32 v25, v106, v154
	v_fmac_f32_e32 v18, v106, v158
	v_fmac_f32_e32 v19, v106, v162
	v_fmac_f32_e32 v24, v107, v151
	v_fmac_f32_e32 v25, v107, v155
	v_fmac_f32_e32 v18, v107, v159
	v_fmac_f32_e32 v19, v107, v163
	ds_read_b128 v[148:151], v2 offset:16800
	ds_read_b128 v[152:155], v2 offset:20896
	ds_read_b128 v[156:159], v2 offset:24992
	ds_read_b128 v[160:163], v2 offset:29088
	s_waitcnt lgkmcnt(8)
	v_fmac_f32_e32 v22, v104, v164
	v_fmac_f32_e32 v23, v104, v168
	v_fmac_f32_e32 v26, v104, v172
	v_fmac_f32_e32 v27, v104, v176
	v_fmac_f32_e32 v22, v105, v165
	v_fmac_f32_e32 v23, v105, v169
	v_fmac_f32_e32 v26, v105, v173
	v_fmac_f32_e32 v27, v105, v177
	v_fmac_f32_e32 v22, v106, v166
	v_fmac_f32_e32 v23, v106, v170
	v_fmac_f32_e32 v26, v106, v174
	v_fmac_f32_e32 v27, v106, v178
	v_fmac_f32_e32 v22, v107, v167
	v_fmac_f32_e32 v23, v107, v171
	v_fmac_f32_e32 v26, v107, v175
	v_fmac_f32_e32 v27, v107, v179
	ds_read_b128 v[164:167], v2 offset:33184
	ds_read_b128 v[168:171], v2 offset:37280
	ds_read_b128 v[172:175], v2 offset:41376
	ds_read_b128 v[176:179], v2 offset:45472
	s_waitcnt lgkmcnt(8)
	v_fmac_f32_e32 v12, v108, v28
	v_fmac_f32_e32 v13, v108, v32
	v_fmac_f32_e32 v14, v108, v36
	v_fmac_f32_e32 v15, v108, v40
	v_fmac_f32_e32 v12, v109, v29
	v_fmac_f32_e32 v13, v109, v33
	v_fmac_f32_e32 v14, v109, v37
	v_fmac_f32_e32 v15, v109, v41
	v_fmac_f32_e32 v12, v110, v30
	v_fmac_f32_e32 v13, v110, v34
	v_fmac_f32_e32 v14, v110, v38
	v_fmac_f32_e32 v15, v110, v42
	v_fmac_f32_e32 v12, v111, v31
	v_fmac_f32_e32 v13, v111, v35
	v_fmac_f32_e32 v14, v111, v39
	v_fmac_f32_e32 v15, v111, v43
	ds_read_b128 v[28:31], v2 offset:49568
	ds_read_b128 v[32:35], v2 offset:53664
	ds_read_b128 v[36:39], v2 offset:57760
	ds_read_b128 v[40:43], v2 offset:61856
	s_waitcnt lgkmcnt(8)
	v_fmac_f32_e32 v16, v108, v148
	v_fmac_f32_e32 v17, v108, v152
	v_fmac_f32_e32 v20, v108, v156
	v_fmac_f32_e32 v21, v108, v160
	v_fmac_f32_e32 v16, v109, v149
	v_fmac_f32_e32 v17, v109, v153
	v_fmac_f32_e32 v20, v109, v157
	v_fmac_f32_e32 v21, v109, v161
	v_fmac_f32_e32 v16, v110, v150
	v_fmac_f32_e32 v17, v110, v154
	v_fmac_f32_e32 v20, v110, v158
	v_fmac_f32_e32 v21, v110, v162
	v_fmac_f32_e32 v16, v111, v151
	v_fmac_f32_e32 v17, v111, v155
	v_fmac_f32_e32 v20, v111, v159
	v_fmac_f32_e32 v21, v111, v163
	ds_read_b128 v[148:151], v2 offset:432
	ds_read_b128 v[152:155], v2 offset:4528
	ds_read_b128 v[156:159], v2 offset:8624
	ds_read_b128 v[160:163], v2 offset:12720
	s_waitcnt lgkmcnt(8)
	v_fmac_f32_e32 v24, v108, v164
	v_fmac_f32_e32 v25, v108, v168
	v_fmac_f32_e32 v18, v108, v172
	v_fmac_f32_e32 v19, v108, v176
	v_fmac_f32_e32 v24, v109, v165
	v_fmac_f32_e32 v25, v109, v169
	v_fmac_f32_e32 v18, v109, v173
	v_fmac_f32_e32 v19, v109, v177
	v_fmac_f32_e32 v24, v110, v166
	v_fmac_f32_e32 v25, v110, v170
	v_fmac_f32_e32 v18, v110, v174
	v_fmac_f32_e32 v19, v110, v178
	v_fmac_f32_e32 v24, v111, v167
	v_fmac_f32_e32 v25, v111, v171
	v_fmac_f32_e32 v18, v111, v175
	v_fmac_f32_e32 v19, v111, v179
	ds_read_b128 v[164:167], v2 offset:16816
	ds_read_b128 v[168:171], v2 offset:20912
	ds_read_b128 v[172:175], v2 offset:25008
	ds_read_b128 v[176:179], v2 offset:29104
	s_waitcnt lgkmcnt(8)
	v_fmac_f32_e32 v22, v108, v28
	v_fmac_f32_e32 v23, v108, v32
	v_fmac_f32_e32 v26, v108, v36
	v_fmac_f32_e32 v27, v108, v40
	v_fmac_f32_e32 v22, v109, v29
	v_fmac_f32_e32 v23, v109, v33
	v_fmac_f32_e32 v26, v109, v37
	v_fmac_f32_e32 v27, v109, v41
	v_fmac_f32_e32 v22, v110, v30
	v_fmac_f32_e32 v23, v110, v34
	v_fmac_f32_e32 v26, v110, v38
	v_fmac_f32_e32 v27, v110, v42
	v_fmac_f32_e32 v22, v111, v31
	v_fmac_f32_e32 v23, v111, v35
	v_fmac_f32_e32 v26, v111, v39
	v_fmac_f32_e32 v27, v111, v43
	ds_read_b128 v[28:31], v2 offset:33200
	ds_read_b128 v[32:35], v2 offset:37296
	ds_read_b128 v[36:39], v2 offset:41392
	ds_read_b128 v[40:43], v2 offset:45488
	s_waitcnt lgkmcnt(8)
	v_fmac_f32_e32 v12, v112, v148
	v_fmac_f32_e32 v13, v112, v152
	v_fmac_f32_e32 v14, v112, v156
	v_fmac_f32_e32 v15, v112, v160
	v_fmac_f32_e32 v12, v113, v149
	v_fmac_f32_e32 v13, v113, v153
	v_fmac_f32_e32 v14, v113, v157
	v_fmac_f32_e32 v15, v113, v161
	v_fmac_f32_e32 v12, v114, v150
	v_fmac_f32_e32 v13, v114, v154
	v_fmac_f32_e32 v14, v114, v158
	v_fmac_f32_e32 v15, v114, v162
	v_fmac_f32_e32 v12, v115, v151
	v_fmac_f32_e32 v13, v115, v155
	v_fmac_f32_e32 v14, v115, v159
	v_fmac_f32_e32 v15, v115, v163
	ds_read_b128 v[148:151], v2 offset:49584
	ds_read_b128 v[152:155], v2 offset:53680
	ds_read_b128 v[156:159], v2 offset:57776
	ds_read_b128 v[160:163], v2 offset:61872
	s_waitcnt lgkmcnt(8)
	v_fmac_f32_e32 v16, v112, v164
	v_fmac_f32_e32 v17, v112, v168
	v_fmac_f32_e32 v20, v112, v172
	v_fmac_f32_e32 v21, v112, v176
	v_fmac_f32_e32 v16, v113, v165
	v_fmac_f32_e32 v17, v113, v169
	v_fmac_f32_e32 v20, v113, v173
	v_fmac_f32_e32 v21, v113, v177
	v_fmac_f32_e32 v16, v114, v166
	v_fmac_f32_e32 v17, v114, v170
	v_fmac_f32_e32 v20, v114, v174
	v_fmac_f32_e32 v21, v114, v178
	v_fmac_f32_e32 v16, v115, v167
	v_fmac_f32_e32 v17, v115, v171
	v_fmac_f32_e32 v20, v115, v175
	v_fmac_f32_e32 v21, v115, v179
	ds_read_b128 v[164:167], v2 offset:448
	ds_read_b128 v[168:171], v2 offset:4544
	ds_read_b128 v[172:175], v2 offset:8640
	ds_read_b128 v[176:179], v2 offset:12736
	s_waitcnt lgkmcnt(8)
	v_fmac_f32_e32 v24, v112, v28
	v_fmac_f32_e32 v25, v112, v32
	v_fmac_f32_e32 v18, v112, v36
	v_fmac_f32_e32 v19, v112, v40
	v_fmac_f32_e32 v24, v113, v29
	v_fmac_f32_e32 v25, v113, v33
	v_fmac_f32_e32 v18, v113, v37
	v_fmac_f32_e32 v19, v113, v41
	v_fmac_f32_e32 v24, v114, v30
	v_fmac_f32_e32 v25, v114, v34
	v_fmac_f32_e32 v18, v114, v38
	v_fmac_f32_e32 v19, v114, v42
	v_fmac_f32_e32 v24, v115, v31
	v_fmac_f32_e32 v25, v115, v35
	v_fmac_f32_e32 v18, v115, v39
	v_fmac_f32_e32 v19, v115, v43
	ds_read_b128 v[28:31], v2 offset:16832
	ds_read_b128 v[32:35], v2 offset:20928
	ds_read_b128 v[36:39], v2 offset:25024
	ds_read_b128 v[40:43], v2 offset:29120
	s_waitcnt lgkmcnt(8)
	v_fmac_f32_e32 v22, v112, v148
	v_fmac_f32_e32 v23, v112, v152
	v_fmac_f32_e32 v26, v112, v156
	v_fmac_f32_e32 v27, v112, v160
	v_fmac_f32_e32 v22, v113, v149
	v_fmac_f32_e32 v23, v113, v153
	v_fmac_f32_e32 v26, v113, v157
	v_fmac_f32_e32 v27, v113, v161
	v_fmac_f32_e32 v22, v114, v150
	v_fmac_f32_e32 v23, v114, v154
	v_fmac_f32_e32 v26, v114, v158
	v_fmac_f32_e32 v27, v114, v162
	v_fmac_f32_e32 v22, v115, v151
	v_fmac_f32_e32 v23, v115, v155
	v_fmac_f32_e32 v26, v115, v159
	v_fmac_f32_e32 v27, v115, v163
	s_waitcnt vmcnt(0)
	ds_read_b128 v[148:151], v2 offset:33216
	ds_read_b128 v[152:155], v2 offset:37312
	ds_read_b128 v[156:159], v2 offset:41408
	ds_read_b128 v[160:163], v2 offset:45504
	s_waitcnt lgkmcnt(8)
	v_fmac_f32_e32 v12, v116, v164
	v_fmac_f32_e32 v13, v116, v168
	v_fmac_f32_e32 v14, v116, v172
	v_fmac_f32_e32 v15, v116, v176
	v_fmac_f32_e32 v12, v117, v165
	v_fmac_f32_e32 v13, v117, v169
	v_fmac_f32_e32 v14, v117, v173
	v_fmac_f32_e32 v15, v117, v177
	v_fmac_f32_e32 v12, v118, v166
	v_fmac_f32_e32 v13, v118, v170
	v_fmac_f32_e32 v14, v118, v174
	v_fmac_f32_e32 v15, v118, v178
	v_fmac_f32_e32 v12, v119, v167
	v_fmac_f32_e32 v13, v119, v171
	v_fmac_f32_e32 v14, v119, v175
	v_fmac_f32_e32 v15, v119, v179
	ds_read_b128 v[164:167], v2 offset:49600
	ds_read_b128 v[168:171], v2 offset:53696
	ds_read_b128 v[172:175], v2 offset:57792
	ds_read_b128 v[176:179], v2 offset:61888
	s_waitcnt lgkmcnt(8)
	v_fmac_f32_e32 v16, v116, v28
	v_fmac_f32_e32 v17, v116, v32
	v_fmac_f32_e32 v20, v116, v36
	v_fmac_f32_e32 v21, v116, v40
	v_fmac_f32_e32 v16, v117, v29
	v_fmac_f32_e32 v17, v117, v33
	v_fmac_f32_e32 v20, v117, v37
	v_fmac_f32_e32 v21, v117, v41
	v_fmac_f32_e32 v16, v118, v30
	v_fmac_f32_e32 v17, v118, v34
	v_fmac_f32_e32 v20, v118, v38
	v_fmac_f32_e32 v21, v118, v42
	v_fmac_f32_e32 v16, v119, v31
	v_fmac_f32_e32 v17, v119, v35
	v_fmac_f32_e32 v20, v119, v39
	v_fmac_f32_e32 v21, v119, v43
	ds_read_b128 v[28:31], v2 offset:464
	ds_read_b128 v[32:35], v2 offset:4560
	ds_read_b128 v[36:39], v2 offset:8656
	ds_read_b128 v[40:43], v2 offset:12752
	s_waitcnt lgkmcnt(8)
	v_fmac_f32_e32 v24, v116, v148
	v_fmac_f32_e32 v25, v116, v152
	v_fmac_f32_e32 v18, v116, v156
	v_fmac_f32_e32 v19, v116, v160
	v_fmac_f32_e32 v24, v117, v149
	v_fmac_f32_e32 v25, v117, v153
	v_fmac_f32_e32 v18, v117, v157
	v_fmac_f32_e32 v19, v117, v161
	v_fmac_f32_e32 v24, v118, v150
	v_fmac_f32_e32 v25, v118, v154
	v_fmac_f32_e32 v18, v118, v158
	v_fmac_f32_e32 v19, v118, v162
	v_fmac_f32_e32 v24, v119, v151
	v_fmac_f32_e32 v25, v119, v155
	v_fmac_f32_e32 v18, v119, v159
	v_fmac_f32_e32 v19, v119, v163
	ds_read_b128 v[148:151], v2 offset:16848
	ds_read_b128 v[152:155], v2 offset:20944
	ds_read_b128 v[156:159], v2 offset:25040
	ds_read_b128 v[160:163], v2 offset:29136
	s_waitcnt lgkmcnt(8)
	v_fmac_f32_e32 v22, v116, v164
	v_fmac_f32_e32 v23, v116, v168
	v_fmac_f32_e32 v26, v116, v172
	v_fmac_f32_e32 v27, v116, v176
	v_fmac_f32_e32 v22, v117, v165
	v_fmac_f32_e32 v23, v117, v169
	v_fmac_f32_e32 v26, v117, v173
	v_fmac_f32_e32 v27, v117, v177
	v_fmac_f32_e32 v22, v118, v166
	v_fmac_f32_e32 v23, v118, v170
	v_fmac_f32_e32 v26, v118, v174
	v_fmac_f32_e32 v27, v118, v178
	v_fmac_f32_e32 v22, v119, v167
	v_fmac_f32_e32 v23, v119, v171
	v_fmac_f32_e32 v26, v119, v175
	v_fmac_f32_e32 v27, v119, v179
	ds_read_b128 v[164:167], v2 offset:33232
	ds_read_b128 v[168:171], v2 offset:37328
	ds_read_b128 v[172:175], v2 offset:41424
	ds_read_b128 v[176:179], v2 offset:45520
	s_waitcnt lgkmcnt(8)
	v_fmac_f32_e32 v12, v120, v28
	v_fmac_f32_e32 v13, v120, v32
	v_fmac_f32_e32 v14, v120, v36
	v_fmac_f32_e32 v15, v120, v40
	v_fmac_f32_e32 v12, v121, v29
	v_fmac_f32_e32 v13, v121, v33
	v_fmac_f32_e32 v14, v121, v37
	v_fmac_f32_e32 v15, v121, v41
	v_fmac_f32_e32 v12, v122, v30
	v_fmac_f32_e32 v13, v122, v34
	v_fmac_f32_e32 v14, v122, v38
	v_fmac_f32_e32 v15, v122, v42
	v_fmac_f32_e32 v12, v123, v31
	v_fmac_f32_e32 v13, v123, v35
	v_fmac_f32_e32 v14, v123, v39
	v_fmac_f32_e32 v15, v123, v43
	ds_read_b128 v[28:31], v2 offset:49616
	ds_read_b128 v[32:35], v2 offset:53712
	ds_read_b128 v[36:39], v2 offset:57808
	ds_read_b128 v[40:43], v2 offset:61904
	s_waitcnt lgkmcnt(8)
	v_fmac_f32_e32 v16, v120, v148
	v_fmac_f32_e32 v17, v120, v152
	v_fmac_f32_e32 v20, v120, v156
	v_fmac_f32_e32 v21, v120, v160
	v_fmac_f32_e32 v16, v121, v149
	v_fmac_f32_e32 v17, v121, v153
	v_fmac_f32_e32 v20, v121, v157
	v_fmac_f32_e32 v21, v121, v161
	v_fmac_f32_e32 v16, v122, v150
	v_fmac_f32_e32 v17, v122, v154
	v_fmac_f32_e32 v20, v122, v158
	v_fmac_f32_e32 v21, v122, v162
	v_fmac_f32_e32 v16, v123, v151
	v_fmac_f32_e32 v17, v123, v155
	v_fmac_f32_e32 v20, v123, v159
	v_fmac_f32_e32 v21, v123, v163
	ds_read_b128 v[148:151], v2 offset:480
	ds_read_b128 v[152:155], v2 offset:4576
	ds_read_b128 v[156:159], v2 offset:8672
	ds_read_b128 v[160:163], v2 offset:12768
	s_waitcnt lgkmcnt(8)
	v_fmac_f32_e32 v24, v120, v164
	v_fmac_f32_e32 v25, v120, v168
	v_fmac_f32_e32 v18, v120, v172
	v_fmac_f32_e32 v19, v120, v176
	v_fmac_f32_e32 v24, v121, v165
	v_fmac_f32_e32 v25, v121, v169
	v_fmac_f32_e32 v18, v121, v173
	v_fmac_f32_e32 v19, v121, v177
	v_fmac_f32_e32 v24, v122, v166
	v_fmac_f32_e32 v25, v122, v170
	v_fmac_f32_e32 v18, v122, v174
	v_fmac_f32_e32 v19, v122, v178
	v_fmac_f32_e32 v24, v123, v167
	v_fmac_f32_e32 v25, v123, v171
	v_fmac_f32_e32 v18, v123, v175
	v_fmac_f32_e32 v19, v123, v179
	ds_read_b128 v[164:167], v2 offset:16864
	ds_read_b128 v[168:171], v2 offset:20960
	ds_read_b128 v[172:175], v2 offset:25056
	ds_read_b128 v[176:179], v2 offset:29152
	s_waitcnt lgkmcnt(8)
	v_fmac_f32_e32 v22, v120, v28
	v_fmac_f32_e32 v23, v120, v32
	v_fmac_f32_e32 v26, v120, v36
	v_fmac_f32_e32 v27, v120, v40
	v_fmac_f32_e32 v22, v121, v29
	v_fmac_f32_e32 v23, v121, v33
	v_fmac_f32_e32 v26, v121, v37
	v_fmac_f32_e32 v27, v121, v41
	v_fmac_f32_e32 v22, v122, v30
	v_fmac_f32_e32 v23, v122, v34
	v_fmac_f32_e32 v26, v122, v38
	v_fmac_f32_e32 v27, v122, v42
	v_fmac_f32_e32 v22, v123, v31
	v_fmac_f32_e32 v23, v123, v35
	v_fmac_f32_e32 v26, v123, v39
	v_fmac_f32_e32 v27, v123, v43
	ds_read_b128 v[28:31], v2 offset:33248
	ds_read_b128 v[32:35], v2 offset:37344
	ds_read_b128 v[36:39], v2 offset:41440
	ds_read_b128 v[40:43], v2 offset:45536
	s_waitcnt lgkmcnt(8)
	v_fmac_f32_e32 v12, v124, v148
	v_fmac_f32_e32 v13, v124, v152
	v_fmac_f32_e32 v14, v124, v156
	v_fmac_f32_e32 v15, v124, v160
	v_fmac_f32_e32 v12, v125, v149
	v_fmac_f32_e32 v13, v125, v153
	v_fmac_f32_e32 v14, v125, v157
	v_fmac_f32_e32 v15, v125, v161
	v_fmac_f32_e32 v12, v126, v150
	v_fmac_f32_e32 v13, v126, v154
	v_fmac_f32_e32 v14, v126, v158
	v_fmac_f32_e32 v15, v126, v162
	v_fmac_f32_e32 v12, v127, v151
	v_fmac_f32_e32 v13, v127, v155
	v_fmac_f32_e32 v14, v127, v159
	v_fmac_f32_e32 v15, v127, v163
	ds_read_b128 v[148:151], v2 offset:49632
	ds_read_b128 v[152:155], v2 offset:53728
	ds_read_b128 v[156:159], v2 offset:57824
	ds_read_b128 v[160:163], v2 offset:61920
	s_waitcnt lgkmcnt(8)
	v_fmac_f32_e32 v16, v124, v164
	v_fmac_f32_e32 v17, v124, v168
	v_fmac_f32_e32 v20, v124, v172
	v_fmac_f32_e32 v21, v124, v176
	v_fmac_f32_e32 v16, v125, v165
	v_fmac_f32_e32 v17, v125, v169
	v_fmac_f32_e32 v20, v125, v173
	v_fmac_f32_e32 v21, v125, v177
	v_fmac_f32_e32 v16, v126, v166
	v_fmac_f32_e32 v17, v126, v170
	v_fmac_f32_e32 v20, v126, v174
	v_fmac_f32_e32 v21, v126, v178
	v_fmac_f32_e32 v16, v127, v167
	v_fmac_f32_e32 v17, v127, v171
	v_fmac_f32_e32 v20, v127, v175
	v_fmac_f32_e32 v21, v127, v179
	ds_read_b128 v[164:167], v2 offset:496
	ds_read_b128 v[168:171], v2 offset:4592
	ds_read_b128 v[172:175], v2 offset:8688
	ds_read_b128 v[176:179], v2 offset:12784
	s_waitcnt lgkmcnt(8)
	v_fmac_f32_e32 v24, v124, v28
	v_fmac_f32_e32 v25, v124, v32
	v_fmac_f32_e32 v18, v124, v36
	v_fmac_f32_e32 v19, v124, v40
	v_fmac_f32_e32 v24, v125, v29
	v_fmac_f32_e32 v25, v125, v33
	v_fmac_f32_e32 v18, v125, v37
	v_fmac_f32_e32 v19, v125, v41
	v_fmac_f32_e32 v24, v126, v30
	v_fmac_f32_e32 v25, v126, v34
	v_fmac_f32_e32 v18, v126, v38
	v_fmac_f32_e32 v19, v126, v42
	v_fmac_f32_e32 v24, v127, v31
	v_fmac_f32_e32 v25, v127, v35
	v_fmac_f32_e32 v18, v127, v39
	v_fmac_f32_e32 v19, v127, v43
	ds_read_b128 v[28:31], v2 offset:16880
	ds_read_b128 v[32:35], v2 offset:20976
	ds_read_b128 v[36:39], v2 offset:25072
	ds_read_b128 v[40:43], v2 offset:29168
	s_waitcnt lgkmcnt(8)
	v_fmac_f32_e32 v22, v124, v148
	v_fmac_f32_e32 v23, v124, v152
	v_fmac_f32_e32 v26, v124, v156
	v_fmac_f32_e32 v27, v124, v160
	v_fmac_f32_e32 v22, v125, v149
	v_fmac_f32_e32 v23, v125, v153
	v_fmac_f32_e32 v26, v125, v157
	v_fmac_f32_e32 v27, v125, v161
	v_fmac_f32_e32 v22, v126, v150
	v_fmac_f32_e32 v23, v126, v154
	v_fmac_f32_e32 v26, v126, v158
	v_fmac_f32_e32 v27, v126, v162
	v_fmac_f32_e32 v22, v127, v151
	v_fmac_f32_e32 v23, v127, v155
	v_fmac_f32_e32 v26, v127, v159
	v_fmac_f32_e32 v27, v127, v163
	ds_read_b128 v[148:151], v2 offset:33264
	ds_read_b128 v[152:155], v2 offset:37360
	ds_read_b128 v[156:159], v2 offset:41456
	ds_read_b128 v[160:163], v2 offset:45552
	s_waitcnt lgkmcnt(8)
	v_fmac_f32_e32 v12, v128, v164
	v_fmac_f32_e32 v13, v128, v168
	v_fmac_f32_e32 v14, v128, v172
	v_fmac_f32_e32 v15, v128, v176
	v_fmac_f32_e32 v12, v129, v165
	v_fmac_f32_e32 v13, v129, v169
	v_fmac_f32_e32 v14, v129, v173
	v_fmac_f32_e32 v15, v129, v177
	v_fmac_f32_e32 v12, v130, v166
	v_fmac_f32_e32 v13, v130, v170
	v_fmac_f32_e32 v14, v130, v174
	v_fmac_f32_e32 v15, v130, v178
	v_fmac_f32_e32 v12, v131, v167
	v_fmac_f32_e32 v13, v131, v171
	v_fmac_f32_e32 v14, v131, v175
	v_fmac_f32_e32 v15, v131, v179
	ds_read_b128 v[164:167], v2 offset:49648
	ds_read_b128 v[168:171], v2 offset:53744
	ds_read_b128 v[172:175], v2 offset:57840
	ds_read_b128 v[176:179], v2 offset:61936
	s_waitcnt lgkmcnt(8)
	v_fmac_f32_e32 v16, v128, v28
	v_fmac_f32_e32 v17, v128, v32
	v_fmac_f32_e32 v20, v128, v36
	v_fmac_f32_e32 v21, v128, v40
	v_fmac_f32_e32 v16, v129, v29
	v_fmac_f32_e32 v17, v129, v33
	v_fmac_f32_e32 v20, v129, v37
	v_fmac_f32_e32 v21, v129, v41
	v_fmac_f32_e32 v16, v130, v30
	v_fmac_f32_e32 v17, v130, v34
	v_fmac_f32_e32 v20, v130, v38
	v_fmac_f32_e32 v21, v130, v42
	v_fmac_f32_e32 v16, v131, v31
	v_fmac_f32_e32 v17, v131, v35
	v_fmac_f32_e32 v20, v131, v39
	v_fmac_f32_e32 v21, v131, v43
	s_waitcnt lgkmcnt(4)
	v_fmac_f32_e32 v24, v128, v148
	v_fmac_f32_e32 v25, v128, v152
	v_fmac_f32_e32 v18, v128, v156
	v_fmac_f32_e32 v19, v128, v160
	v_fmac_f32_e32 v24, v129, v149
	v_fmac_f32_e32 v25, v129, v153
	v_fmac_f32_e32 v18, v129, v157
	v_fmac_f32_e32 v19, v129, v161
	v_fmac_f32_e32 v24, v130, v150
	v_fmac_f32_e32 v25, v130, v154
	v_fmac_f32_e32 v18, v130, v158
	v_fmac_f32_e32 v19, v130, v162
	v_fmac_f32_e32 v24, v131, v151
	v_fmac_f32_e32 v25, v131, v155
	v_fmac_f32_e32 v18, v131, v159
	v_fmac_f32_e32 v19, v131, v163
	s_waitcnt lgkmcnt(0)
	v_fmac_f32_e32 v22, v128, v164
	v_fmac_f32_e32 v23, v128, v168
	v_fmac_f32_e32 v26, v128, v172
	v_fmac_f32_e32 v27, v128, v176
	v_fmac_f32_e32 v22, v129, v165
	v_fmac_f32_e32 v23, v129, v169
	v_fmac_f32_e32 v26, v129, v173
	v_fmac_f32_e32 v27, v129, v177
	v_fmac_f32_e32 v22, v130, v166
	v_fmac_f32_e32 v23, v130, v170
	v_fmac_f32_e32 v26, v130, v174
	v_fmac_f32_e32 v27, v130, v178
	v_fmac_f32_e32 v22, v131, v167
	v_fmac_f32_e32 v23, v131, v171
	v_fmac_f32_e32 v26, v131, v175
	v_fmac_f32_e32 v27, v131, v179
	s_lshl_b32 s2, s55, 12
	s_add_i32 s2, s2, 0
	v_lshl_add_u32 v0, v231, 2, s2
	s_movk_i32 s2, 0x400
	v_add_u32_e32 v0, 0x10000, v0
	v_cmp_gt_i32_e32 vcc, s2, v190
	ds_write2st64_b32 v0, v12, v13 offset1:1
	ds_write2st64_b32 v0, v14, v15 offset0:2 offset1:3
	ds_write2st64_b32 v0, v16, v17 offset0:4 offset1:5
	ds_write2st64_b32 v0, v20, v21 offset0:6 offset1:7
	ds_write2st64_b32 v0, v24, v25 offset0:8 offset1:9
	ds_write2st64_b32 v0, v18, v19 offset0:10 offset1:11
	ds_write2st64_b32 v0, v22, v23 offset0:12 offset1:13
	ds_write2st64_b32 v0, v26, v27 offset0:14 offset1:15
	s_waitcnt lgkmcnt(0)
	s_barrier
	s_and_saveexec_b64 s[12:13], vcc
	s_movk_i32 s4, 0x1ff
	s_cbranch_execz .LBB0_306
	v_readlane_b32 s84, v254, 40
	v_readlane_b32 s88, v254, 44
	v_readlane_b32 s89, v254, 45
	s_add_i32 s2, 0, 0x10000
	s_mov_b64 s[18:19], 0
	v_lshl_add_u64 v[0:1], v[96:97], 2, s[88:89]
	v_lshlrev_b32_e32 v96, 2, v231
	v_add_u32_e32 v4, s2, v96
	v_readlane_b32 s2, v250, 13
	v_readlane_b32 s3, v250, 14
	v_mov_b32_e32 v5, v190
	v_readlane_b32 s85, v254, 41
	v_lshl_add_u64 v[2:3], s[2:3], 0, v[96:97]
	v_readlane_b32 s86, v254, 42
	v_readlane_b32 s87, v254, 43
	v_readlane_b32 s90, v254, 46
	v_readlane_b32 s91, v254, 47
